# v066 + the four kstep-advanced LDS-DMA pieces per iteration (uq/ukv/G_OUT/G_UP fully, G_IN/G_DN one each) in saddr form with offset:128 and M0-128; their 64-bit VALU adds removed
# baseline (speedup 1.0000x reference)
.Lrx_G_IN_0:
	s_waitcnt vmcnt(16)
	s_waitcnt lgkmcnt(0)
	s_setprio 1
	s_barrier
	v_mfma_f32_16x16x32_bf16 v[126:129], v[130:133], v[188:191], v[126:129]
	v_mfma_f32_16x16x32_bf16 v[122:125], v[164:167], v[188:191], v[122:125]
	v_mfma_f32_16x16x32_bf16 v[110:113], v[130:133], v[196:199], v[110:113]
	v_mfma_f32_16x16x32_bf16 v[106:109], v[164:167], v[196:199], v[106:109]
	v_mfma_f32_16x16x32_bf16 v[92:95], v[130:133], v[214:217], v[92:95]
	v_mfma_f32_16x16x32_bf16 v[88:91], v[164:167], v[214:217], v[88:91]
	v_mfma_f32_16x16x32_bf16 v[76:79], v[130:133], v[222:225], v[76:79]
	v_mfma_f32_16x16x32_bf16 v[72:75], v[164:167], v[222:225], v[72:75]
	v_mfma_f32_16x16x32_bf16 v[126:129], v[160:163], v[192:195], v[126:129]
	v_mfma_f32_16x16x32_bf16 v[122:125], v[168:171], v[192:195], v[122:125]
	v_mfma_f32_16x16x32_bf16 v[110:113], v[160:163], v[210:213], v[110:113]
	v_mfma_f32_16x16x32_bf16 v[106:109], v[168:171], v[210:213], v[106:109]
	v_mfma_f32_16x16x32_bf16 v[92:95], v[160:163], v[218:221], v[92:95]
	v_mfma_f32_16x16x32_bf16 v[88:91], v[168:171], v[218:221], v[88:91]
	v_mfma_f32_16x16x32_bf16 v[76:79], v[160:163], v[226:229], v[76:79]
	v_mfma_f32_16x16x32_bf16 v[72:75], v[168:171], v[226:229], v[72:75]
	v_mfma_f32_16x16x32_bf16 v[118:121], v[172:175], v[188:191], v[118:121]
	v_mfma_f32_16x16x32_bf16 v[114:117], v[180:183], v[188:191], v[114:117]
	v_mfma_f32_16x16x32_bf16 v[102:105], v[172:175], v[196:199], v[102:105]
	v_mfma_f32_16x16x32_bf16 v[98:101], v[180:183], v[196:199], v[98:101]
	v_mfma_f32_16x16x32_bf16 v[84:87], v[172:175], v[214:217], v[84:87]
	v_mfma_f32_16x16x32_bf16 v[80:83], v[180:183], v[214:217], v[80:83]
	v_mfma_f32_16x16x32_bf16 v[68:71], v[172:175], v[222:225], v[68:71]
	v_mfma_f32_16x16x32_bf16 v[64:67], v[180:183], v[222:225], v[64:67]
	v_mfma_f32_16x16x32_bf16 v[118:121], v[176:179], v[192:195], v[118:121]
	v_mfma_f32_16x16x32_bf16 v[114:117], v[184:187], v[192:195], v[114:117]
	v_mfma_f32_16x16x32_bf16 v[102:105], v[176:179], v[210:213], v[102:105]
	v_mfma_f32_16x16x32_bf16 v[98:101], v[184:187], v[210:213], v[98:101]
	v_mfma_f32_16x16x32_bf16 v[84:87], v[176:179], v[218:221], v[84:87]
	v_mfma_f32_16x16x32_bf16 v[80:83], v[184:187], v[218:221], v[80:83]
	v_mfma_f32_16x16x32_bf16 v[68:71], v[176:179], v[226:229], v[68:71]
	v_mfma_f32_16x16x32_bf16 v[64:67], v[184:187], v[226:229], v[64:67]
	s_barrier
	s_setprio 0
	s_add_i32 s55, s55, s75
	s_mov_b32 m0, s55
	ds_read_b128 v[188:191], v159 offset:16384
	ds_read_b128 v[192:195], v159 offset:17408
	ds_read_b128 v[196:199], v159 offset:18432
	ds_read_b128 v[210:213], v159 offset:19456
	ds_read_b128 v[214:217], v159 offset:20480
	ds_read_b128 v[218:221], v159 offset:21504
	ds_read_b128 v[222:225], v159 offset:22528
	ds_read_b128 v[226:229], v159 offset:23552
	global_load_lds_dwordx4 v142, s[44:45]
	s_add_i32 m0, s55, 0x2000
	s_add_u32 s56, s44, 0x80000
	v_lshl_add_u64 v[154:155], s[44:45], 0, v[138:139]
	s_addc_u32 s57, s45, 0
	s_add_i32 s55, s61, s75
	global_load_lds_dwordx4 v138, s[44:45]
	s_mov_b32 m0, s55
	v_lshl_add_u64 v[202:203], s[52:53], 0, v[140:141]
	global_load_lds_dwordx4 v142, s[56:57]
	s_add_i32 m0, s55, 0x2000
	s_nop 0
	global_load_lds_dwordx4 v138, s[56:57]
	v_lshl_add_u64 v[156:157], s[52:53], 0, v[144:145]
	s_mov_b32 m0, s35
	s_nop 0
	global_load_lds_dwordx4 v144, s[52:53]
	s_mov_b32 m0, s68
	s_nop 0
	global_load_lds_dwordx4 v140, s[52:53]
	v_cmp_ne_u32_e32 vcc, 0, v243
	s_cbranch_vccnz .Lrx_G_IN_1
	s_waitcnt vmcnt(8)
.Lrx_G_IN_1:
	s_waitcnt vmcnt(16)
	v_mov_b32_e32 v243, 0
	s_waitcnt lgkmcnt(0)
	s_setprio 1
	s_barrier
	v_mfma_f32_16x16x32_bf16 v[60:63], v[130:133], v[188:191], v[60:63]
	v_mfma_f32_16x16x32_bf16 v[56:59], v[164:167], v[188:191], v[56:59]
	v_mfma_f32_16x16x32_bf16 v[44:47], v[130:133], v[196:199], v[44:47]
	v_mfma_f32_16x16x32_bf16 v[40:43], v[164:167], v[196:199], v[40:43]
	v_mfma_f32_16x16x32_bf16 v[28:31], v[130:133], v[214:217], v[28:31]
	v_mfma_f32_16x16x32_bf16 v[24:27], v[164:167], v[214:217], v[24:27]
	v_mfma_f32_16x16x32_bf16 v[12:15], v[130:133], v[222:225], v[12:15]
	v_mfma_f32_16x16x32_bf16 v[8:11], v[164:167], v[222:225], v[8:11]
	v_mfma_f32_16x16x32_bf16 v[60:63], v[160:163], v[192:195], v[60:63]
	v_mfma_f32_16x16x32_bf16 v[56:59], v[168:171], v[192:195], v[56:59]
	v_mfma_f32_16x16x32_bf16 v[44:47], v[160:163], v[210:213], v[44:47]
	v_mfma_f32_16x16x32_bf16 v[40:43], v[168:171], v[210:213], v[40:43]
	v_mfma_f32_16x16x32_bf16 v[28:31], v[160:163], v[218:221], v[28:31]
	v_mfma_f32_16x16x32_bf16 v[24:27], v[168:171], v[218:221], v[24:27]
	v_mfma_f32_16x16x32_bf16 v[12:15], v[160:163], v[226:229], v[12:15]
	v_mfma_f32_16x16x32_bf16 v[8:11], v[168:171], v[226:229], v[8:11]
	v_mfma_f32_16x16x32_bf16 v[52:55], v[172:175], v[188:191], v[52:55]
	v_mfma_f32_16x16x32_bf16 v[48:51], v[180:183], v[188:191], v[48:51]
	v_mfma_f32_16x16x32_bf16 v[36:39], v[172:175], v[196:199], v[36:39]
	v_mfma_f32_16x16x32_bf16 v[32:35], v[180:183], v[196:199], v[32:35]
	v_mfma_f32_16x16x32_bf16 v[20:23], v[172:175], v[214:217], v[20:23]
	v_mfma_f32_16x16x32_bf16 v[16:19], v[180:183], v[214:217], v[16:19]
	v_mfma_f32_16x16x32_bf16 v[4:7], v[172:175], v[222:225], v[4:7]
	v_mfma_f32_16x16x32_bf16 v[0:3], v[180:183], v[222:225], v[0:3]
	v_mfma_f32_16x16x32_bf16 v[52:55], v[176:179], v[192:195], v[52:55]
	v_mfma_f32_16x16x32_bf16 v[48:51], v[184:187], v[192:195], v[48:51]
	v_mfma_f32_16x16x32_bf16 v[36:39], v[176:179], v[210:213], v[36:39]
	v_mfma_f32_16x16x32_bf16 v[32:35], v[184:187], v[210:213], v[32:35]
	v_mfma_f32_16x16x32_bf16 v[20:23], v[176:179], v[218:221], v[20:23]
	v_mfma_f32_16x16x32_bf16 v[16:19], v[184:187], v[218:221], v[16:19]
	v_mfma_f32_16x16x32_bf16 v[4:7], v[176:179], v[226:229], v[4:7]
	v_mfma_f32_16x16x32_bf16 v[0:3], v[184:187], v[226:229], v[0:3]
	s_barrier
	s_setprio 0
	s_add_i32 s55, 0, 0x18000
	s_add_i32 s56, 0, 0x1c000
	v_add_u32_e32 v168, s55, v158
	v_add_u32_e32 v184, s56, v158
	ds_read_b128 v[130:133], v168
	ds_read_b128 v[160:163], v168 offset:1024
	ds_read_b128 v[164:167], v168 offset:2048
	ds_read_b128 v[168:171], v168 offset:3072
	ds_read_b128 v[172:175], v184
	ds_read_b128 v[176:179], v184 offset:1024
	ds_read_b128 v[180:183], v184 offset:2048
	ds_read_b128 v[184:187], v184 offset:3072
	s_add_u32 s52, s52, 0x80000
	s_addc_u32 s53, s53, 0
	s_mov_b32 m0, s69
	ds_read_b128 v[188:191], v159 offset:32768
	ds_read_b128 v[192:195], v159 offset:33792
	ds_read_b128 v[196:199], v159 offset:34816
	ds_read_b128 v[210:213], v159 offset:35840
	ds_read_b128 v[214:217], v159 offset:36864
	ds_read_b128 v[218:221], v159 offset:37888
	ds_read_b128 v[222:225], v159 offset:38912
	ds_read_b128 v[226:229], v159 offset:39936
	global_load_lds_dwordx4 v144, s[52:53]
	s_mov_b32 m0, s77
	s_nop 0
	global_load_lds_dwordx4 v140, s[52:53]
	s_waitcnt vmcnt(8)
	s_waitcnt lgkmcnt(0)
	s_setprio 1
	s_barrier
	v_mfma_f32_16x16x32_bf16 v[126:129], v[130:133], v[188:191], v[126:129]
	v_mfma_f32_16x16x32_bf16 v[122:125], v[164:167], v[188:191], v[122:125]
	v_mfma_f32_16x16x32_bf16 v[110:113], v[130:133], v[196:199], v[110:113]
	v_mfma_f32_16x16x32_bf16 v[106:109], v[164:167], v[196:199], v[106:109]
	v_mfma_f32_16x16x32_bf16 v[92:95], v[130:133], v[214:217], v[92:95]
	v_mfma_f32_16x16x32_bf16 v[88:91], v[164:167], v[214:217], v[88:91]
	v_mfma_f32_16x16x32_bf16 v[76:79], v[130:133], v[222:225], v[76:79]
	v_mfma_f32_16x16x32_bf16 v[72:75], v[164:167], v[222:225], v[72:75]
	v_mfma_f32_16x16x32_bf16 v[126:129], v[160:163], v[192:195], v[126:129]
	v_mfma_f32_16x16x32_bf16 v[122:125], v[168:171], v[192:195], v[122:125]
	v_mfma_f32_16x16x32_bf16 v[110:113], v[160:163], v[210:213], v[110:113]
	v_mfma_f32_16x16x32_bf16 v[106:109], v[168:171], v[210:213], v[106:109]
	v_mfma_f32_16x16x32_bf16 v[92:95], v[160:163], v[218:221], v[92:95]
	v_mfma_f32_16x16x32_bf16 v[88:91], v[168:171], v[218:221], v[88:91]
	v_mfma_f32_16x16x32_bf16 v[76:79], v[160:163], v[226:229], v[76:79]
	v_mfma_f32_16x16x32_bf16 v[72:75], v[168:171], v[226:229], v[72:75]
	v_mfma_f32_16x16x32_bf16 v[118:121], v[172:175], v[188:191], v[118:121]
	v_mfma_f32_16x16x32_bf16 v[114:117], v[180:183], v[188:191], v[114:117]
	v_mfma_f32_16x16x32_bf16 v[102:105], v[172:175], v[196:199], v[102:105]
	v_mfma_f32_16x16x32_bf16 v[98:101], v[180:183], v[196:199], v[98:101]
	v_mfma_f32_16x16x32_bf16 v[84:87], v[172:175], v[214:217], v[84:87]
	v_mfma_f32_16x16x32_bf16 v[80:83], v[180:183], v[214:217], v[80:83]
	v_mfma_f32_16x16x32_bf16 v[68:71], v[172:175], v[222:225], v[68:71]
	v_mfma_f32_16x16x32_bf16 v[64:67], v[180:183], v[222:225], v[64:67]
	v_mfma_f32_16x16x32_bf16 v[118:121], v[176:179], v[192:195], v[118:121]
	v_mfma_f32_16x16x32_bf16 v[114:117], v[184:187], v[192:195], v[114:117]
	v_mfma_f32_16x16x32_bf16 v[102:105], v[176:179], v[210:213], v[102:105]
	v_mfma_f32_16x16x32_bf16 v[98:101], v[184:187], v[210:213], v[98:101]
	v_mfma_f32_16x16x32_bf16 v[84:87], v[176:179], v[218:221], v[84:87]
	v_mfma_f32_16x16x32_bf16 v[80:83], v[184:187], v[218:221], v[80:83]
	v_mfma_f32_16x16x32_bf16 v[68:71], v[176:179], v[226:229], v[68:71]
	v_mfma_f32_16x16x32_bf16 v[64:67], v[184:187], v[226:229], v[64:67]
	s_barrier
	s_setprio 0
	s_add_i32 s52, s55, s75
	s_add_i32 m0, s52, 0xffffff80
	ds_read_b128 v[188:191], v159 offset:49152
	ds_read_b128 v[192:195], v159 offset:50176
	ds_read_b128 v[196:199], v159 offset:51200
	ds_read_b128 v[210:213], v159 offset:52224
	ds_read_b128 v[214:217], v159 offset:53248
	ds_read_b128 v[218:221], v159 offset:54272
	ds_read_b128 v[222:225], v159 offset:55296
	ds_read_b128 v[226:229], v159 offset:56320
	global_load_lds_dwordx4 v142, s[44:45] offset:128
	s_add_i32 m0, s52, 0x2000
	s_add_u32 s44, s44, 0x80080
	v_lshl_add_u64 v[150:151], v[154:155], 0, s[64:65]
	s_addc_u32 s45, s45, 0
	s_add_i32 s52, s56, s75
	global_load_lds_dwordx4 v[150:151], off
	s_mov_b32 m0, s52
	s_nop 0
	global_load_lds_dwordx4 v142, s[44:45]
	s_add_i32 m0, s52, 0x2000
	s_nop 0
	global_load_lds_dwordx4 v138, s[44:45]
	v_lshl_add_u64 v[150:151], v[156:157], 0, s[64:65]
	s_mov_b32 m0, s79
	s_nop 0
	global_load_lds_dwordx4 v[150:151], off
	v_lshl_add_u64 v[150:151], v[202:203], 0, s[64:65]
	s_mov_b32 m0, s81
	s_nop 0
	global_load_lds_dwordx4 v[150:151], off
	s_waitcnt vmcnt(8)
	s_waitcnt lgkmcnt(0)
	s_setprio 1
	s_barrier
	v_mfma_f32_16x16x32_bf16 v[60:63], v[130:133], v[188:191], v[60:63]
	v_mfma_f32_16x16x32_bf16 v[56:59], v[164:167], v[188:191], v[56:59]
	v_mfma_f32_16x16x32_bf16 v[44:47], v[130:133], v[196:199], v[44:47]
	v_mfma_f32_16x16x32_bf16 v[40:43], v[164:167], v[196:199], v[40:43]
	v_mfma_f32_16x16x32_bf16 v[28:31], v[130:133], v[214:217], v[28:31]
	v_mfma_f32_16x16x32_bf16 v[24:27], v[164:167], v[214:217], v[24:27]
	v_mfma_f32_16x16x32_bf16 v[12:15], v[130:133], v[222:225], v[12:15]
	v_mfma_f32_16x16x32_bf16 v[8:11], v[164:167], v[222:225], v[8:11]
	v_mfma_f32_16x16x32_bf16 v[60:63], v[160:163], v[192:195], v[60:63]
	v_mfma_f32_16x16x32_bf16 v[56:59], v[168:171], v[192:195], v[56:59]
	v_mfma_f32_16x16x32_bf16 v[44:47], v[160:163], v[210:213], v[44:47]
	v_mfma_f32_16x16x32_bf16 v[40:43], v[168:171], v[210:213], v[40:43]
	v_mfma_f32_16x16x32_bf16 v[28:31], v[160:163], v[218:221], v[28:31]
	v_mfma_f32_16x16x32_bf16 v[24:27], v[168:171], v[218:221], v[24:27]
	v_mfma_f32_16x16x32_bf16 v[12:15], v[160:163], v[226:229], v[12:15]
	v_mfma_f32_16x16x32_bf16 v[8:11], v[168:171], v[226:229], v[8:11]
	v_mfma_f32_16x16x32_bf16 v[52:55], v[172:175], v[188:191], v[52:55]
	v_mfma_f32_16x16x32_bf16 v[48:51], v[180:183], v[188:191], v[48:51]
	v_mfma_f32_16x16x32_bf16 v[36:39], v[172:175], v[196:199], v[36:39]
	v_mfma_f32_16x16x32_bf16 v[32:35], v[180:183], v[196:199], v[32:35]
	v_mfma_f32_16x16x32_bf16 v[20:23], v[172:175], v[214:217], v[20:23]
	v_mfma_f32_16x16x32_bf16 v[16:19], v[180:183], v[214:217], v[16:19]
	v_mfma_f32_16x16x32_bf16 v[4:7], v[172:175], v[222:225], v[4:7]
	v_mfma_f32_16x16x32_bf16 v[0:3], v[180:183], v[222:225], v[0:3]
	v_mfma_f32_16x16x32_bf16 v[52:55], v[176:179], v[192:195], v[52:55]
	v_mfma_f32_16x16x32_bf16 v[48:51], v[184:187], v[192:195], v[48:51]
	v_mfma_f32_16x16x32_bf16 v[36:39], v[176:179], v[210:213], v[36:39]
	v_mfma_f32_16x16x32_bf16 v[32:35], v[184:187], v[210:213], v[32:35]
	v_mfma_f32_16x16x32_bf16 v[20:23], v[176:179], v[218:221], v[20:23]
	v_mfma_f32_16x16x32_bf16 v[16:19], v[184:187], v[218:221], v[16:19]
	v_mfma_f32_16x16x32_bf16 v[4:7], v[176:179], v[226:229], v[4:7]
	v_mfma_f32_16x16x32_bf16 v[0:3], v[184:187], v[226:229], v[0:3]
	s_barrier
	s_setprio 0
	s_add_i32 s54, s54, 2
	s_add_u32 s42, s42, 0x100
	s_addc_u32 s43, s43, 0
	s_add_u32 s28, s28, 0x100
	s_addc_u32 s33, s33, 0
	s_cmp_gt_u32 s54, 29
	s_cbranch_scc0 .LBB0_352
	v_mov_b32_e32 v243, 1
	v_readlane_b32 s6, v251, 54
	v_readlane_b32 s7, v251, 55
	s_and_b64 vcc, exec, s[6:7]
	s_cbranch_vccz .LBB0_355
	s_barrier

.Lrx_uq_0:
	s_waitcnt vmcnt(24)
	s_waitcnt lgkmcnt(0)
	s_setprio 1
	s_barrier
	v_mfma_f32_16x16x32_bf16 v[126:129], v[146:149], v[182:185], v[126:129]
	v_mfma_f32_16x16x32_bf16 v[122:125], v[158:161], v[182:185], v[122:125]
	v_mfma_f32_16x16x32_bf16 v[118:121], v[146:149], v[190:193], v[118:121]
	v_mfma_f32_16x16x32_bf16 v[114:117], v[158:161], v[190:193], v[114:117]
	v_mfma_f32_16x16x32_bf16 v[102:105], v[146:149], v[210:213], v[102:105]
	v_mfma_f32_16x16x32_bf16 v[98:101], v[158:161], v[210:213], v[98:101]
	v_mfma_f32_16x16x32_bf16 v[84:87], v[146:149], v[218:221], v[84:87]
	v_mfma_f32_16x16x32_bf16 v[80:83], v[158:161], v[218:221], v[80:83]
	v_mfma_f32_16x16x32_bf16 v[126:129], v[150:153], v[186:189], v[126:129]
	v_mfma_f32_16x16x32_bf16 v[122:125], v[162:165], v[186:189], v[122:125]
	v_mfma_f32_16x16x32_bf16 v[118:121], v[150:153], v[194:197], v[118:121]
	v_mfma_f32_16x16x32_bf16 v[114:117], v[162:165], v[194:197], v[114:117]
	v_mfma_f32_16x16x32_bf16 v[102:105], v[150:153], v[214:217], v[102:105]
	v_mfma_f32_16x16x32_bf16 v[98:101], v[162:165], v[214:217], v[98:101]
	v_mfma_f32_16x16x32_bf16 v[84:87], v[150:153], v[222:225], v[84:87]
	v_mfma_f32_16x16x32_bf16 v[80:83], v[162:165], v[222:225], v[80:83]
	v_mfma_f32_16x16x32_bf16 v[110:113], v[166:169], v[182:185], v[110:113]
	v_mfma_f32_16x16x32_bf16 v[106:109], v[174:177], v[182:185], v[106:109]
	v_mfma_f32_16x16x32_bf16 v[92:95], v[166:169], v[190:193], v[92:95]
	v_mfma_f32_16x16x32_bf16 v[88:91], v[174:177], v[190:193], v[88:91]
	v_mfma_f32_16x16x32_bf16 v[76:79], v[166:169], v[210:213], v[76:79]
	v_mfma_f32_16x16x32_bf16 v[72:75], v[174:177], v[210:213], v[72:75]
	v_mfma_f32_16x16x32_bf16 v[68:71], v[166:169], v[218:221], v[68:71]
	v_mfma_f32_16x16x32_bf16 v[64:67], v[174:177], v[218:221], v[64:67]
	v_mfma_f32_16x16x32_bf16 v[110:113], v[170:173], v[186:189], v[110:113]
	v_mfma_f32_16x16x32_bf16 v[106:109], v[178:181], v[186:189], v[106:109]
	v_mfma_f32_16x16x32_bf16 v[92:95], v[170:173], v[194:197], v[92:95]
	v_mfma_f32_16x16x32_bf16 v[88:91], v[178:181], v[194:197], v[88:91]
	v_mfma_f32_16x16x32_bf16 v[76:79], v[170:173], v[214:217], v[76:79]
	v_mfma_f32_16x16x32_bf16 v[72:75], v[178:181], v[214:217], v[72:75]
	v_mfma_f32_16x16x32_bf16 v[68:71], v[170:173], v[222:225], v[68:71]
	v_mfma_f32_16x16x32_bf16 v[64:67], v[178:181], v[222:225], v[64:67]
	s_barrier
	s_setprio 0
	s_add_i32 s56, s58, s75
	s_mov_b32 m0, s56
	ds_read_b128 v[182:185], v144 offset:16384
	ds_read_b128 v[186:189], v144 offset:17408
	ds_read_b128 v[190:193], v144 offset:18432
	ds_read_b128 v[194:197], v144 offset:19456
	ds_read_b128 v[210:213], v144 offset:20480
	ds_read_b128 v[214:217], v144 offset:21504
	ds_read_b128 v[218:221], v144 offset:22528
	ds_read_b128 v[222:225], v144 offset:23552
	global_load_lds_dwordx4 v96, s[82:83]
	s_add_i32 m0, s56, 0x2000
	s_add_u32 s56, s82, 0x20000
	s_addc_u32 s57, s83, 0
	s_add_i32 s58, s59, s75
	global_load_lds_dwordx4 v130, s[82:83]
	s_mov_b32 m0, s58
	s_nop 0
	global_load_lds_dwordx4 v96, s[56:57]
	s_add_i32 m0, s58, 0x2000
	s_nop 0
	global_load_lds_dwordx4 v130, s[56:57]
	s_mov_b32 m0, s10
	s_nop 0
	global_load_lds_dwordx4 v134, s[84:85]
	s_mov_b32 m0, s12
	s_nop 0
	global_load_lds_dwordx4 v132, s[84:85]
	v_cmp_ne_u32_e32 vcc, 0, v243
	s_cbranch_vccnz .Lrx_uq_1
	s_waitcnt vmcnt(8)
.Lrx_uq_1:
	s_waitcnt vmcnt(24)
	v_mov_b32_e32 v243, 0
	s_waitcnt lgkmcnt(0)
	s_setprio 1
	s_barrier
	v_mfma_f32_16x16x32_bf16 v[60:63], v[146:149], v[182:185], v[60:63]
	v_mfma_f32_16x16x32_bf16 v[56:59], v[158:161], v[182:185], v[56:59]
	v_mfma_f32_16x16x32_bf16 v[52:55], v[146:149], v[190:193], v[52:55]
	v_mfma_f32_16x16x32_bf16 v[48:51], v[158:161], v[190:193], v[48:51]
	v_mfma_f32_16x16x32_bf16 v[36:39], v[146:149], v[210:213], v[36:39]
	v_mfma_f32_16x16x32_bf16 v[32:35], v[158:161], v[210:213], v[32:35]
	v_mfma_f32_16x16x32_bf16 v[20:23], v[146:149], v[218:221], v[20:23]
	v_mfma_f32_16x16x32_bf16 v[16:19], v[158:161], v[218:221], v[16:19]
	v_mfma_f32_16x16x32_bf16 v[60:63], v[150:153], v[186:189], v[60:63]
	v_mfma_f32_16x16x32_bf16 v[56:59], v[162:165], v[186:189], v[56:59]
	v_mfma_f32_16x16x32_bf16 v[52:55], v[150:153], v[194:197], v[52:55]
	v_mfma_f32_16x16x32_bf16 v[48:51], v[162:165], v[194:197], v[48:51]
	v_mfma_f32_16x16x32_bf16 v[36:39], v[150:153], v[214:217], v[36:39]
	v_mfma_f32_16x16x32_bf16 v[32:35], v[162:165], v[214:217], v[32:35]
	v_mfma_f32_16x16x32_bf16 v[20:23], v[150:153], v[222:225], v[20:23]
	v_mfma_f32_16x16x32_bf16 v[16:19], v[162:165], v[222:225], v[16:19]
	v_mfma_f32_16x16x32_bf16 v[44:47], v[166:169], v[182:185], v[44:47]
	v_mfma_f32_16x16x32_bf16 v[40:43], v[174:177], v[182:185], v[40:43]
	v_mfma_f32_16x16x32_bf16 v[28:31], v[166:169], v[190:193], v[28:31]
	v_mfma_f32_16x16x32_bf16 v[24:27], v[174:177], v[190:193], v[24:27]
	v_mfma_f32_16x16x32_bf16 v[12:15], v[166:169], v[210:213], v[12:15]
	v_mfma_f32_16x16x32_bf16 v[8:11], v[174:177], v[210:213], v[8:11]
	v_mfma_f32_16x16x32_bf16 v[4:7], v[166:169], v[218:221], v[4:7]
	v_mfma_f32_16x16x32_bf16 v[0:3], v[174:177], v[218:221], v[0:3]
	v_mfma_f32_16x16x32_bf16 v[44:47], v[170:173], v[186:189], v[44:47]
	v_mfma_f32_16x16x32_bf16 v[40:43], v[178:181], v[186:189], v[40:43]
	v_mfma_f32_16x16x32_bf16 v[28:31], v[170:173], v[194:197], v[28:31]
	v_mfma_f32_16x16x32_bf16 v[24:27], v[178:181], v[194:197], v[24:27]
	v_mfma_f32_16x16x32_bf16 v[12:15], v[170:173], v[214:217], v[12:15]
	v_mfma_f32_16x16x32_bf16 v[8:11], v[178:181], v[214:217], v[8:11]
	v_mfma_f32_16x16x32_bf16 v[4:7], v[170:173], v[222:225], v[4:7]
	v_mfma_f32_16x16x32_bf16 v[0:3], v[178:181], v[222:225], v[0:3]
	s_barrier
	s_setprio 0
	s_add_i32 s58, 0, 0x18000
	v_add_u32_e32 v145, s58, v142
	s_add_i32 s59, 0, 0x1c000
	ds_read_b128 v[146:149], v145
	ds_read_b128 v[150:153], v145 offset:1024
	ds_read_b128 v[158:161], v145 offset:2048
	ds_read_b128 v[162:165], v145 offset:3072
	v_add_u32_e32 v145, s59, v142
	ds_read_b128 v[166:169], v145
	ds_read_b128 v[170:173], v145 offset:1024
	ds_read_b128 v[174:177], v145 offset:2048
	ds_read_b128 v[178:181], v145 offset:3072
	s_add_u32 s56, s84, 0x20000
	s_addc_u32 s57, s85, 0
	s_mov_b32 m0, s18
	ds_read_b128 v[182:185], v144 offset:32768
	ds_read_b128 v[186:189], v144 offset:33792
	ds_read_b128 v[190:193], v144 offset:34816
	ds_read_b128 v[194:197], v144 offset:35840
	ds_read_b128 v[210:213], v144 offset:36864
	ds_read_b128 v[214:217], v144 offset:37888
	ds_read_b128 v[218:221], v144 offset:38912
	ds_read_b128 v[222:225], v144 offset:39936
	global_load_lds_dwordx4 v134, s[56:57]
	s_mov_b32 m0, s20
	s_nop 0
	global_load_lds_dwordx4 v132, s[56:57]
	s_waitcnt vmcnt(8)
	s_waitcnt lgkmcnt(0)
	s_setprio 1
	s_barrier
	v_mfma_f32_16x16x32_bf16 v[126:129], v[146:149], v[182:185], v[126:129]
	v_mfma_f32_16x16x32_bf16 v[122:125], v[158:161], v[182:185], v[122:125]
	v_mfma_f32_16x16x32_bf16 v[118:121], v[146:149], v[190:193], v[118:121]
	v_mfma_f32_16x16x32_bf16 v[114:117], v[158:161], v[190:193], v[114:117]
	v_mfma_f32_16x16x32_bf16 v[102:105], v[146:149], v[210:213], v[102:105]
	v_mfma_f32_16x16x32_bf16 v[98:101], v[158:161], v[210:213], v[98:101]
	v_mfma_f32_16x16x32_bf16 v[84:87], v[146:149], v[218:221], v[84:87]
	v_mfma_f32_16x16x32_bf16 v[80:83], v[158:161], v[218:221], v[80:83]
	v_mfma_f32_16x16x32_bf16 v[126:129], v[150:153], v[186:189], v[126:129]
	v_mfma_f32_16x16x32_bf16 v[122:125], v[162:165], v[186:189], v[122:125]
	v_mfma_f32_16x16x32_bf16 v[118:121], v[150:153], v[194:197], v[118:121]
	v_mfma_f32_16x16x32_bf16 v[114:117], v[162:165], v[194:197], v[114:117]
	v_mfma_f32_16x16x32_bf16 v[102:105], v[150:153], v[214:217], v[102:105]
	v_mfma_f32_16x16x32_bf16 v[98:101], v[162:165], v[214:217], v[98:101]
	v_mfma_f32_16x16x32_bf16 v[84:87], v[150:153], v[222:225], v[84:87]
	v_mfma_f32_16x16x32_bf16 v[80:83], v[162:165], v[222:225], v[80:83]
	v_mfma_f32_16x16x32_bf16 v[110:113], v[166:169], v[182:185], v[110:113]
	v_mfma_f32_16x16x32_bf16 v[106:109], v[174:177], v[182:185], v[106:109]
	v_mfma_f32_16x16x32_bf16 v[92:95], v[166:169], v[190:193], v[92:95]
	v_mfma_f32_16x16x32_bf16 v[88:91], v[174:177], v[190:193], v[88:91]
	v_mfma_f32_16x16x32_bf16 v[76:79], v[166:169], v[210:213], v[76:79]
	v_mfma_f32_16x16x32_bf16 v[72:75], v[174:177], v[210:213], v[72:75]
	v_mfma_f32_16x16x32_bf16 v[68:71], v[166:169], v[218:221], v[68:71]
	v_mfma_f32_16x16x32_bf16 v[64:67], v[174:177], v[218:221], v[64:67]
	v_mfma_f32_16x16x32_bf16 v[110:113], v[170:173], v[186:189], v[110:113]
	v_mfma_f32_16x16x32_bf16 v[106:109], v[178:181], v[186:189], v[106:109]
	v_mfma_f32_16x16x32_bf16 v[92:95], v[170:173], v[194:197], v[92:95]
	v_mfma_f32_16x16x32_bf16 v[88:91], v[178:181], v[194:197], v[88:91]
	v_mfma_f32_16x16x32_bf16 v[76:79], v[170:173], v[214:217], v[76:79]
	v_mfma_f32_16x16x32_bf16 v[72:75], v[178:181], v[214:217], v[72:75]
	v_mfma_f32_16x16x32_bf16 v[68:71], v[170:173], v[222:225], v[68:71]
	v_mfma_f32_16x16x32_bf16 v[64:67], v[178:181], v[222:225], v[64:67]
	s_barrier
	s_setprio 0
	s_add_i32 s56, s58, s75
	s_add_i32 m0, s56, 0xffffff80
	ds_read_b128 v[182:185], v144 offset:49152
	ds_read_b128 v[186:189], v144 offset:50176
	ds_read_b128 v[190:193], v144 offset:51200
	ds_read_b128 v[194:197], v144 offset:52224
	ds_read_b128 v[210:213], v144 offset:53248
	ds_read_b128 v[214:217], v144 offset:54272
	ds_read_b128 v[218:221], v144 offset:55296
	ds_read_b128 v[222:225], v144 offset:56320
	global_load_lds_dwordx4 v96, s[82:83] offset:128
	s_add_i32 m0, s56, 0x1f80
	s_add_u32 s56, s82, 0x20080
	s_addc_u32 s57, s83, 0
	s_add_i32 s58, s59, s75
	global_load_lds_dwordx4 v130, s[82:83] offset:128
	s_mov_b32 m0, s58
	s_nop 0
	global_load_lds_dwordx4 v96, s[56:57]
	s_add_i32 m0, s58, 0x2000
	s_nop 0
	global_load_lds_dwordx4 v130, s[56:57]
	s_add_i32 m0, s26, 0xffffff80
	s_nop 0
	global_load_lds_dwordx4 v134, s[84:85] offset:128
	s_add_i32 m0, s27, 0xffffff80
	s_nop 0
	global_load_lds_dwordx4 v132, s[84:85] offset:128
	s_waitcnt vmcnt(8)
	s_waitcnt lgkmcnt(0)
	s_setprio 1
	s_barrier
	v_mfma_f32_16x16x32_bf16 v[60:63], v[146:149], v[182:185], v[60:63]
	v_mfma_f32_16x16x32_bf16 v[56:59], v[158:161], v[182:185], v[56:59]
	v_mfma_f32_16x16x32_bf16 v[52:55], v[146:149], v[190:193], v[52:55]
	v_mfma_f32_16x16x32_bf16 v[48:51], v[158:161], v[190:193], v[48:51]
	v_mfma_f32_16x16x32_bf16 v[36:39], v[146:149], v[210:213], v[36:39]
	v_mfma_f32_16x16x32_bf16 v[32:35], v[158:161], v[210:213], v[32:35]
	v_mfma_f32_16x16x32_bf16 v[20:23], v[146:149], v[218:221], v[20:23]
	v_mfma_f32_16x16x32_bf16 v[16:19], v[158:161], v[218:221], v[16:19]
	v_mfma_f32_16x16x32_bf16 v[60:63], v[150:153], v[186:189], v[60:63]
	v_mfma_f32_16x16x32_bf16 v[56:59], v[162:165], v[186:189], v[56:59]
	v_mfma_f32_16x16x32_bf16 v[52:55], v[150:153], v[194:197], v[52:55]
	v_mfma_f32_16x16x32_bf16 v[48:51], v[162:165], v[194:197], v[48:51]
	v_mfma_f32_16x16x32_bf16 v[36:39], v[150:153], v[214:217], v[36:39]
	v_mfma_f32_16x16x32_bf16 v[32:35], v[162:165], v[214:217], v[32:35]
	v_mfma_f32_16x16x32_bf16 v[20:23], v[150:153], v[222:225], v[20:23]
	v_mfma_f32_16x16x32_bf16 v[16:19], v[162:165], v[222:225], v[16:19]
	v_mfma_f32_16x16x32_bf16 v[44:47], v[166:169], v[182:185], v[44:47]
	v_mfma_f32_16x16x32_bf16 v[40:43], v[174:177], v[182:185], v[40:43]
	v_mfma_f32_16x16x32_bf16 v[28:31], v[166:169], v[190:193], v[28:31]
	v_mfma_f32_16x16x32_bf16 v[24:27], v[174:177], v[190:193], v[24:27]
	v_mfma_f32_16x16x32_bf16 v[12:15], v[166:169], v[210:213], v[12:15]
	v_mfma_f32_16x16x32_bf16 v[8:11], v[174:177], v[210:213], v[8:11]
	v_mfma_f32_16x16x32_bf16 v[4:7], v[166:169], v[218:221], v[4:7]
	v_mfma_f32_16x16x32_bf16 v[0:3], v[174:177], v[218:221], v[0:3]
	v_mfma_f32_16x16x32_bf16 v[44:47], v[170:173], v[186:189], v[44:47]
	v_mfma_f32_16x16x32_bf16 v[40:43], v[178:181], v[186:189], v[40:43]
	v_mfma_f32_16x16x32_bf16 v[28:31], v[170:173], v[194:197], v[28:31]
	v_mfma_f32_16x16x32_bf16 v[24:27], v[178:181], v[194:197], v[24:27]
	v_mfma_f32_16x16x32_bf16 v[12:15], v[170:173], v[214:217], v[12:15]
	v_mfma_f32_16x16x32_bf16 v[8:11], v[178:181], v[214:217], v[8:11]
	v_mfma_f32_16x16x32_bf16 v[4:7], v[170:173], v[222:225], v[4:7]
	v_mfma_f32_16x16x32_bf16 v[0:3], v[178:181], v[222:225], v[0:3]
	s_barrier
	s_setprio 0
	s_add_i32 s55, s55, 2
	s_add_u32 s68, s68, 0x100
	s_addc_u32 s69, s69, 0
	s_add_u32 s51, s51, 0x100
	s_addc_u32 s54, s54, 0
	s_cmp_gt_u32 s55, 5
	s_cbranch_scc0 .LBB0_636
	v_mov_b32_e32 v243, 1
	v_readlane_b32 s6, v251, 54
	v_readlane_b32 s7, v251, 55
	s_and_b64 vcc, exec, s[6:7]
	s_cbranch_vccz .LBB0_639
	s_barrier

.Lrx_ukv_0:
	s_waitcnt vmcnt(24)
	s_waitcnt lgkmcnt(0)
	s_setprio 1
	s_barrier
	v_mfma_f32_16x16x32_bf16 v[126:129], v[146:149], v[182:185], v[126:129]
	v_mfma_f32_16x16x32_bf16 v[122:125], v[158:161], v[182:185], v[122:125]
	v_mfma_f32_16x16x32_bf16 v[118:121], v[146:149], v[190:193], v[118:121]
	v_mfma_f32_16x16x32_bf16 v[114:117], v[158:161], v[190:193], v[114:117]
	v_mfma_f32_16x16x32_bf16 v[102:105], v[146:149], v[210:213], v[102:105]
	v_mfma_f32_16x16x32_bf16 v[98:101], v[158:161], v[210:213], v[98:101]
	v_mfma_f32_16x16x32_bf16 v[84:87], v[146:149], v[218:221], v[84:87]
	v_mfma_f32_16x16x32_bf16 v[80:83], v[158:161], v[218:221], v[80:83]
	v_mfma_f32_16x16x32_bf16 v[126:129], v[150:153], v[186:189], v[126:129]
	v_mfma_f32_16x16x32_bf16 v[122:125], v[162:165], v[186:189], v[122:125]
	v_mfma_f32_16x16x32_bf16 v[118:121], v[150:153], v[194:197], v[118:121]
	v_mfma_f32_16x16x32_bf16 v[114:117], v[162:165], v[194:197], v[114:117]
	v_mfma_f32_16x16x32_bf16 v[102:105], v[150:153], v[214:217], v[102:105]
	v_mfma_f32_16x16x32_bf16 v[98:101], v[162:165], v[214:217], v[98:101]
	v_mfma_f32_16x16x32_bf16 v[84:87], v[150:153], v[222:225], v[84:87]
	v_mfma_f32_16x16x32_bf16 v[80:83], v[162:165], v[222:225], v[80:83]
	v_mfma_f32_16x16x32_bf16 v[110:113], v[166:169], v[182:185], v[110:113]
	v_mfma_f32_16x16x32_bf16 v[106:109], v[174:177], v[182:185], v[106:109]
	v_mfma_f32_16x16x32_bf16 v[92:95], v[166:169], v[190:193], v[92:95]
	v_mfma_f32_16x16x32_bf16 v[88:91], v[174:177], v[190:193], v[88:91]
	v_mfma_f32_16x16x32_bf16 v[76:79], v[166:169], v[210:213], v[76:79]
	v_mfma_f32_16x16x32_bf16 v[72:75], v[174:177], v[210:213], v[72:75]
	v_mfma_f32_16x16x32_bf16 v[68:71], v[166:169], v[218:221], v[68:71]
	v_mfma_f32_16x16x32_bf16 v[64:67], v[174:177], v[218:221], v[64:67]
	v_mfma_f32_16x16x32_bf16 v[110:113], v[170:173], v[186:189], v[110:113]
	v_mfma_f32_16x16x32_bf16 v[106:109], v[178:181], v[186:189], v[106:109]
	v_mfma_f32_16x16x32_bf16 v[92:95], v[170:173], v[194:197], v[92:95]
	v_mfma_f32_16x16x32_bf16 v[88:91], v[178:181], v[194:197], v[88:91]
	v_mfma_f32_16x16x32_bf16 v[76:79], v[170:173], v[214:217], v[76:79]
	v_mfma_f32_16x16x32_bf16 v[72:75], v[178:181], v[214:217], v[72:75]
	v_mfma_f32_16x16x32_bf16 v[68:71], v[170:173], v[222:225], v[68:71]
	v_mfma_f32_16x16x32_bf16 v[64:67], v[178:181], v[222:225], v[64:67]
	s_barrier
	s_setprio 0
	s_add_i32 s58, s61, s75
	s_mov_b32 m0, s58
	ds_read_b128 v[182:185], v144 offset:16384
	ds_read_b128 v[186:189], v144 offset:17408
	ds_read_b128 v[190:193], v144 offset:18432
	ds_read_b128 v[194:197], v144 offset:19456
	ds_read_b128 v[210:213], v144 offset:20480
	ds_read_b128 v[214:217], v144 offset:21504
	ds_read_b128 v[218:221], v144 offset:22528
	ds_read_b128 v[222:225], v144 offset:23552
	global_load_lds_dwordx4 v96, s[82:83]
	s_add_i32 m0, s58, 0x2000
	s_add_u32 s58, s82, 0x20000
	s_addc_u32 s59, s83, 0
	s_add_i32 s61, s62, s75
	global_load_lds_dwordx4 v130, s[82:83]
	s_mov_b32 m0, s61
	s_nop 0
	global_load_lds_dwordx4 v96, s[58:59]
	s_add_i32 m0, s61, 0x2000
	s_nop 0
	global_load_lds_dwordx4 v130, s[58:59]
	s_mov_b32 m0, s18
	s_nop 0
	global_load_lds_dwordx4 v134, s[84:85]
	s_mov_b32 m0, s20
	s_nop 0
	global_load_lds_dwordx4 v132, s[84:85]
	v_cmp_ne_u32_e32 vcc, 0, v243
	s_cbranch_vccnz .Lrx_ukv_1
	s_waitcnt vmcnt(8)
.Lrx_ukv_1:
	s_waitcnt vmcnt(24)
	v_mov_b32_e32 v243, 0
	s_waitcnt lgkmcnt(0)
	s_setprio 1
	s_barrier
	v_mfma_f32_16x16x32_bf16 v[60:63], v[146:149], v[182:185], v[60:63]
	v_mfma_f32_16x16x32_bf16 v[56:59], v[158:161], v[182:185], v[56:59]
	v_mfma_f32_16x16x32_bf16 v[52:55], v[146:149], v[190:193], v[52:55]
	v_mfma_f32_16x16x32_bf16 v[48:51], v[158:161], v[190:193], v[48:51]
	v_mfma_f32_16x16x32_bf16 v[36:39], v[146:149], v[210:213], v[36:39]
	v_mfma_f32_16x16x32_bf16 v[32:35], v[158:161], v[210:213], v[32:35]
	v_mfma_f32_16x16x32_bf16 v[20:23], v[146:149], v[218:221], v[20:23]
	v_mfma_f32_16x16x32_bf16 v[16:19], v[158:161], v[218:221], v[16:19]
	v_mfma_f32_16x16x32_bf16 v[60:63], v[150:153], v[186:189], v[60:63]
	v_mfma_f32_16x16x32_bf16 v[56:59], v[162:165], v[186:189], v[56:59]
	v_mfma_f32_16x16x32_bf16 v[52:55], v[150:153], v[194:197], v[52:55]
	v_mfma_f32_16x16x32_bf16 v[48:51], v[162:165], v[194:197], v[48:51]
	v_mfma_f32_16x16x32_bf16 v[36:39], v[150:153], v[214:217], v[36:39]
	v_mfma_f32_16x16x32_bf16 v[32:35], v[162:165], v[214:217], v[32:35]
	v_mfma_f32_16x16x32_bf16 v[20:23], v[150:153], v[222:225], v[20:23]
	v_mfma_f32_16x16x32_bf16 v[16:19], v[162:165], v[222:225], v[16:19]
	v_mfma_f32_16x16x32_bf16 v[44:47], v[166:169], v[182:185], v[44:47]
	v_mfma_f32_16x16x32_bf16 v[40:43], v[174:177], v[182:185], v[40:43]
	v_mfma_f32_16x16x32_bf16 v[28:31], v[166:169], v[190:193], v[28:31]
	v_mfma_f32_16x16x32_bf16 v[24:27], v[174:177], v[190:193], v[24:27]
	v_mfma_f32_16x16x32_bf16 v[12:15], v[166:169], v[210:213], v[12:15]
	v_mfma_f32_16x16x32_bf16 v[8:11], v[174:177], v[210:213], v[8:11]
	v_mfma_f32_16x16x32_bf16 v[4:7], v[166:169], v[218:221], v[4:7]
	v_mfma_f32_16x16x32_bf16 v[0:3], v[174:177], v[218:221], v[0:3]
	v_mfma_f32_16x16x32_bf16 v[44:47], v[170:173], v[186:189], v[44:47]
	v_mfma_f32_16x16x32_bf16 v[40:43], v[178:181], v[186:189], v[40:43]
	v_mfma_f32_16x16x32_bf16 v[28:31], v[170:173], v[194:197], v[28:31]
	v_mfma_f32_16x16x32_bf16 v[24:27], v[178:181], v[194:197], v[24:27]
	v_mfma_f32_16x16x32_bf16 v[12:15], v[170:173], v[214:217], v[12:15]
	v_mfma_f32_16x16x32_bf16 v[8:11], v[178:181], v[214:217], v[8:11]
	v_mfma_f32_16x16x32_bf16 v[4:7], v[170:173], v[222:225], v[4:7]
	v_mfma_f32_16x16x32_bf16 v[0:3], v[178:181], v[222:225], v[0:3]
	s_barrier
	s_setprio 0
	s_add_i32 s61, 0, 0x18000
	v_add_u32_e32 v145, s61, v142
	s_add_i32 s62, 0, 0x1c000
	ds_read_b128 v[146:149], v145
	ds_read_b128 v[150:153], v145 offset:1024
	ds_read_b128 v[158:161], v145 offset:2048
	ds_read_b128 v[162:165], v145 offset:3072
	v_add_u32_e32 v145, s62, v142
	ds_read_b128 v[166:169], v145
	ds_read_b128 v[170:173], v145 offset:1024
	ds_read_b128 v[174:177], v145 offset:2048
	ds_read_b128 v[178:181], v145 offset:3072
	s_add_u32 s58, s84, 0x20000
	s_addc_u32 s59, s85, 0
	s_mov_b32 m0, s26
	ds_read_b128 v[182:185], v144 offset:32768
	ds_read_b128 v[186:189], v144 offset:33792
	ds_read_b128 v[190:193], v144 offset:34816
	ds_read_b128 v[194:197], v144 offset:35840
	ds_read_b128 v[210:213], v144 offset:36864
	ds_read_b128 v[214:217], v144 offset:37888
	ds_read_b128 v[218:221], v144 offset:38912
	ds_read_b128 v[222:225], v144 offset:39936
	global_load_lds_dwordx4 v134, s[58:59]
	s_mov_b32 m0, s27
	s_nop 0
	global_load_lds_dwordx4 v132, s[58:59]
	s_waitcnt vmcnt(8)
	s_waitcnt lgkmcnt(0)
	s_setprio 1
	s_barrier
	v_mfma_f32_16x16x32_bf16 v[126:129], v[146:149], v[182:185], v[126:129]
	v_mfma_f32_16x16x32_bf16 v[122:125], v[158:161], v[182:185], v[122:125]
	v_mfma_f32_16x16x32_bf16 v[118:121], v[146:149], v[190:193], v[118:121]
	v_mfma_f32_16x16x32_bf16 v[114:117], v[158:161], v[190:193], v[114:117]
	v_mfma_f32_16x16x32_bf16 v[102:105], v[146:149], v[210:213], v[102:105]
	v_mfma_f32_16x16x32_bf16 v[98:101], v[158:161], v[210:213], v[98:101]
	v_mfma_f32_16x16x32_bf16 v[84:87], v[146:149], v[218:221], v[84:87]
	v_mfma_f32_16x16x32_bf16 v[80:83], v[158:161], v[218:221], v[80:83]
	v_mfma_f32_16x16x32_bf16 v[126:129], v[150:153], v[186:189], v[126:129]
	v_mfma_f32_16x16x32_bf16 v[122:125], v[162:165], v[186:189], v[122:125]
	v_mfma_f32_16x16x32_bf16 v[118:121], v[150:153], v[194:197], v[118:121]
	v_mfma_f32_16x16x32_bf16 v[114:117], v[162:165], v[194:197], v[114:117]
	v_mfma_f32_16x16x32_bf16 v[102:105], v[150:153], v[214:217], v[102:105]
	v_mfma_f32_16x16x32_bf16 v[98:101], v[162:165], v[214:217], v[98:101]
	v_mfma_f32_16x16x32_bf16 v[84:87], v[150:153], v[222:225], v[84:87]
	v_mfma_f32_16x16x32_bf16 v[80:83], v[162:165], v[222:225], v[80:83]
	v_mfma_f32_16x16x32_bf16 v[110:113], v[166:169], v[182:185], v[110:113]
	v_mfma_f32_16x16x32_bf16 v[106:109], v[174:177], v[182:185], v[106:109]
	v_mfma_f32_16x16x32_bf16 v[92:95], v[166:169], v[190:193], v[92:95]
	v_mfma_f32_16x16x32_bf16 v[88:91], v[174:177], v[190:193], v[88:91]
	v_mfma_f32_16x16x32_bf16 v[76:79], v[166:169], v[210:213], v[76:79]
	v_mfma_f32_16x16x32_bf16 v[72:75], v[174:177], v[210:213], v[72:75]
	v_mfma_f32_16x16x32_bf16 v[68:71], v[166:169], v[218:221], v[68:71]
	v_mfma_f32_16x16x32_bf16 v[64:67], v[174:177], v[218:221], v[64:67]
	v_mfma_f32_16x16x32_bf16 v[110:113], v[170:173], v[186:189], v[110:113]
	v_mfma_f32_16x16x32_bf16 v[106:109], v[178:181], v[186:189], v[106:109]
	v_mfma_f32_16x16x32_bf16 v[92:95], v[170:173], v[194:197], v[92:95]
	v_mfma_f32_16x16x32_bf16 v[88:91], v[178:181], v[194:197], v[88:91]
	v_mfma_f32_16x16x32_bf16 v[76:79], v[170:173], v[214:217], v[76:79]
	v_mfma_f32_16x16x32_bf16 v[72:75], v[178:181], v[214:217], v[72:75]
	v_mfma_f32_16x16x32_bf16 v[68:71], v[170:173], v[222:225], v[68:71]
	v_mfma_f32_16x16x32_bf16 v[64:67], v[178:181], v[222:225], v[64:67]
	s_barrier
	s_setprio 0
	s_add_i32 s58, s61, s75
	s_add_i32 m0, s58, 0xffffff80
	ds_read_b128 v[182:185], v144 offset:49152
	ds_read_b128 v[186:189], v144 offset:50176
	ds_read_b128 v[190:193], v144 offset:51200
	ds_read_b128 v[194:197], v144 offset:52224
	ds_read_b128 v[210:213], v144 offset:53248
	ds_read_b128 v[214:217], v144 offset:54272
	ds_read_b128 v[218:221], v144 offset:55296
	ds_read_b128 v[222:225], v144 offset:56320
	global_load_lds_dwordx4 v96, s[82:83] offset:128
	s_add_i32 m0, s58, 0x1f80
	s_add_u32 s58, s82, 0x20080
	s_addc_u32 s59, s83, 0
	s_add_i32 s61, s62, s75
	global_load_lds_dwordx4 v130, s[82:83] offset:128
	s_mov_b32 m0, s61
	s_nop 0
	global_load_lds_dwordx4 v96, s[58:59]
	s_add_i32 m0, s61, 0x2000
	s_nop 0
	global_load_lds_dwordx4 v130, s[58:59]
	s_add_i32 m0, s28, 0xffffff80
	s_nop 0
	global_load_lds_dwordx4 v134, s[84:85] offset:128
	s_add_i32 m0, s33, 0xffffff80
	s_nop 0
	global_load_lds_dwordx4 v132, s[84:85] offset:128
	s_waitcnt vmcnt(8)
	s_waitcnt lgkmcnt(0)
	s_setprio 1
	s_barrier
	v_mfma_f32_16x16x32_bf16 v[60:63], v[146:149], v[182:185], v[60:63]
	v_mfma_f32_16x16x32_bf16 v[56:59], v[158:161], v[182:185], v[56:59]
	v_mfma_f32_16x16x32_bf16 v[52:55], v[146:149], v[190:193], v[52:55]
	v_mfma_f32_16x16x32_bf16 v[48:51], v[158:161], v[190:193], v[48:51]
	v_mfma_f32_16x16x32_bf16 v[36:39], v[146:149], v[210:213], v[36:39]
	v_mfma_f32_16x16x32_bf16 v[32:35], v[158:161], v[210:213], v[32:35]
	v_mfma_f32_16x16x32_bf16 v[20:23], v[146:149], v[218:221], v[20:23]
	v_mfma_f32_16x16x32_bf16 v[16:19], v[158:161], v[218:221], v[16:19]
	v_mfma_f32_16x16x32_bf16 v[60:63], v[150:153], v[186:189], v[60:63]
	v_mfma_f32_16x16x32_bf16 v[56:59], v[162:165], v[186:189], v[56:59]
	v_mfma_f32_16x16x32_bf16 v[52:55], v[150:153], v[194:197], v[52:55]
	v_mfma_f32_16x16x32_bf16 v[48:51], v[162:165], v[194:197], v[48:51]
	v_mfma_f32_16x16x32_bf16 v[36:39], v[150:153], v[214:217], v[36:39]
	v_mfma_f32_16x16x32_bf16 v[32:35], v[162:165], v[214:217], v[32:35]
	v_mfma_f32_16x16x32_bf16 v[20:23], v[150:153], v[222:225], v[20:23]
	v_mfma_f32_16x16x32_bf16 v[16:19], v[162:165], v[222:225], v[16:19]
	v_mfma_f32_16x16x32_bf16 v[44:47], v[166:169], v[182:185], v[44:47]
	v_mfma_f32_16x16x32_bf16 v[40:43], v[174:177], v[182:185], v[40:43]
	v_mfma_f32_16x16x32_bf16 v[28:31], v[166:169], v[190:193], v[28:31]
	v_mfma_f32_16x16x32_bf16 v[24:27], v[174:177], v[190:193], v[24:27]
	v_mfma_f32_16x16x32_bf16 v[12:15], v[166:169], v[210:213], v[12:15]
	v_mfma_f32_16x16x32_bf16 v[8:11], v[174:177], v[210:213], v[8:11]
	v_mfma_f32_16x16x32_bf16 v[4:7], v[166:169], v[218:221], v[4:7]
	v_mfma_f32_16x16x32_bf16 v[0:3], v[174:177], v[218:221], v[0:3]
	v_mfma_f32_16x16x32_bf16 v[44:47], v[170:173], v[186:189], v[44:47]
	v_mfma_f32_16x16x32_bf16 v[40:43], v[178:181], v[186:189], v[40:43]
	v_mfma_f32_16x16x32_bf16 v[28:31], v[170:173], v[194:197], v[28:31]
	v_mfma_f32_16x16x32_bf16 v[24:27], v[178:181], v[194:197], v[24:27]
	v_mfma_f32_16x16x32_bf16 v[12:15], v[170:173], v[214:217], v[12:15]
	v_mfma_f32_16x16x32_bf16 v[8:11], v[178:181], v[214:217], v[8:11]
	v_mfma_f32_16x16x32_bf16 v[4:7], v[170:173], v[222:225], v[4:7]
	v_mfma_f32_16x16x32_bf16 v[0:3], v[178:181], v[222:225], v[0:3]
	s_barrier
	s_setprio 0
	s_add_i32 s57, s57, 2
	s_add_u32 s68, s68, 0x100
	s_addc_u32 s69, s69, 0
	s_add_u32 s55, s55, 0x100
	s_addc_u32 s56, s56, 0
	s_cmp_gt_u32 s57, 5
	s_cbranch_scc0 .LBB0_656
	v_mov_b32_e32 v243, 1
	v_readlane_b32 s6, v251, 54
	v_readlane_b32 s7, v251, 55
	s_and_b64 vcc, exec, s[6:7]
	s_cbranch_vccz .LBB0_659
	s_barrier

.Lrx_G_OUT_0:
	s_waitcnt vmcnt(44)
	s_waitcnt lgkmcnt(0)
	s_setprio 1
	s_barrier
	v_mfma_f32_16x16x32_bf16 v[126:129], v[130:133], v[184:187], v[126:129]
	v_mfma_f32_16x16x32_bf16 v[122:125], v[152:155], v[184:187], v[122:125]
	v_mfma_f32_16x16x32_bf16 v[110:113], v[130:133], v[192:195], v[110:113]
	v_mfma_f32_16x16x32_bf16 v[106:109], v[152:155], v[192:195], v[106:109]
	v_mfma_f32_16x16x32_bf16 v[92:95], v[130:133], v[202:205], v[92:95]
	v_mfma_f32_16x16x32_bf16 v[88:91], v[152:155], v[202:205], v[88:91]
	v_mfma_f32_16x16x32_bf16 v[76:79], v[130:133], v[214:217], v[76:79]
	v_mfma_f32_16x16x32_bf16 v[72:75], v[152:155], v[214:217], v[72:75]
	v_mfma_f32_16x16x32_bf16 v[126:129], v[134:137], v[188:191], v[126:129]
	v_mfma_f32_16x16x32_bf16 v[122:125], v[156:159], v[188:191], v[122:125]
	v_mfma_f32_16x16x32_bf16 v[110:113], v[134:137], v[196:199], v[110:113]
	v_mfma_f32_16x16x32_bf16 v[106:109], v[156:159], v[196:199], v[106:109]
	v_mfma_f32_16x16x32_bf16 v[92:95], v[134:137], v[210:213], v[92:95]
	v_mfma_f32_16x16x32_bf16 v[88:91], v[156:159], v[210:213], v[88:91]
	v_mfma_f32_16x16x32_bf16 v[76:79], v[134:137], v[218:221], v[76:79]
	v_mfma_f32_16x16x32_bf16 v[72:75], v[156:159], v[218:221], v[72:75]
	v_mfma_f32_16x16x32_bf16 v[118:121], v[160:163], v[184:187], v[118:121]
	v_mfma_f32_16x16x32_bf16 v[114:117], v[176:179], v[184:187], v[114:117]
	v_mfma_f32_16x16x32_bf16 v[102:105], v[160:163], v[192:195], v[102:105]
	v_mfma_f32_16x16x32_bf16 v[98:101], v[176:179], v[192:195], v[98:101]
	v_mfma_f32_16x16x32_bf16 v[84:87], v[160:163], v[202:205], v[84:87]
	v_mfma_f32_16x16x32_bf16 v[80:83], v[176:179], v[202:205], v[80:83]
	v_mfma_f32_16x16x32_bf16 v[68:71], v[160:163], v[214:217], v[68:71]
	v_mfma_f32_16x16x32_bf16 v[64:67], v[176:179], v[214:217], v[64:67]
	v_mfma_f32_16x16x32_bf16 v[118:121], v[172:175], v[188:191], v[118:121]
	v_mfma_f32_16x16x32_bf16 v[114:117], v[180:183], v[188:191], v[114:117]
	v_mfma_f32_16x16x32_bf16 v[102:105], v[172:175], v[196:199], v[102:105]
	v_mfma_f32_16x16x32_bf16 v[98:101], v[180:183], v[196:199], v[98:101]
	v_mfma_f32_16x16x32_bf16 v[84:87], v[172:175], v[210:213], v[84:87]
	v_mfma_f32_16x16x32_bf16 v[80:83], v[180:183], v[210:213], v[80:83]
	v_mfma_f32_16x16x32_bf16 v[68:71], v[172:175], v[218:221], v[68:71]
	v_mfma_f32_16x16x32_bf16 v[64:67], v[180:183], v[218:221], v[64:67]
	s_barrier
	s_setprio 0
	s_add_i32 s34, s38, s75
	s_mov_b32 m0, s34
	ds_read_b128 v[184:187], v171 offset:16384
	ds_read_b128 v[188:191], v171 offset:17408
	ds_read_b128 v[192:195], v171 offset:18432
	ds_read_b128 v[196:199], v171 offset:19456
	ds_read_b128 v[202:205], v171 offset:20480
	ds_read_b128 v[210:213], v171 offset:21504
	ds_read_b128 v[214:217], v171 offset:22528
	ds_read_b128 v[218:221], v171 offset:23552
	global_load_lds_dwordx4 v96, s[84:85]
	s_add_i32 m0, s34, 0x2000
	s_add_u32 s34, s84, 0x80000
	s_addc_u32 s35, s85, 0
	s_add_i32 s38, s39, s75
	global_load_lds_dwordx4 v142, s[84:85]
	s_mov_b32 m0, s38
	s_nop 0
	global_load_lds_dwordx4 v96, s[34:35]
	s_add_i32 m0, s38, 0x2000
	s_nop 0
	global_load_lds_dwordx4 v142, s[34:35]
	s_mov_b32 m0, s58
	s_nop 0
	global_load_lds_dwordx4 v146, s[86:87]
	s_mov_b32 m0, s59
	s_nop 0
	global_load_lds_dwordx4 v144, s[86:87]
	v_cmp_ne_u32_e32 vcc, 0, v243
	s_cbranch_vccnz .Lrx_G_OUT_1
	s_waitcnt vmcnt(8)
.Lrx_G_OUT_1:
	s_waitcnt vmcnt(44)
	v_mov_b32_e32 v243, 0
	s_waitcnt lgkmcnt(0)
	s_setprio 1
	s_barrier
	v_mfma_f32_16x16x32_bf16 v[60:63], v[130:133], v[184:187], v[60:63]
	v_mfma_f32_16x16x32_bf16 v[56:59], v[152:155], v[184:187], v[56:59]
	v_mfma_f32_16x16x32_bf16 v[44:47], v[130:133], v[192:195], v[44:47]
	v_mfma_f32_16x16x32_bf16 v[40:43], v[152:155], v[192:195], v[40:43]
	v_mfma_f32_16x16x32_bf16 v[28:31], v[130:133], v[202:205], v[28:31]
	v_mfma_f32_16x16x32_bf16 v[24:27], v[152:155], v[202:205], v[24:27]
	v_mfma_f32_16x16x32_bf16 v[12:15], v[130:133], v[214:217], v[12:15]
	v_mfma_f32_16x16x32_bf16 v[8:11], v[152:155], v[214:217], v[8:11]
	v_mfma_f32_16x16x32_bf16 v[60:63], v[134:137], v[188:191], v[60:63]
	v_mfma_f32_16x16x32_bf16 v[56:59], v[156:159], v[188:191], v[56:59]
	v_mfma_f32_16x16x32_bf16 v[44:47], v[134:137], v[196:199], v[44:47]
	v_mfma_f32_16x16x32_bf16 v[40:43], v[156:159], v[196:199], v[40:43]
	v_mfma_f32_16x16x32_bf16 v[28:31], v[134:137], v[210:213], v[28:31]
	v_mfma_f32_16x16x32_bf16 v[24:27], v[156:159], v[210:213], v[24:27]
	v_mfma_f32_16x16x32_bf16 v[12:15], v[134:137], v[218:221], v[12:15]
	v_mfma_f32_16x16x32_bf16 v[8:11], v[156:159], v[218:221], v[8:11]
	v_mfma_f32_16x16x32_bf16 v[52:55], v[160:163], v[184:187], v[52:55]
	v_mfma_f32_16x16x32_bf16 v[48:51], v[176:179], v[184:187], v[48:51]
	v_mfma_f32_16x16x32_bf16 v[36:39], v[160:163], v[192:195], v[36:39]
	v_mfma_f32_16x16x32_bf16 v[32:35], v[176:179], v[192:195], v[32:35]
	v_mfma_f32_16x16x32_bf16 v[20:23], v[160:163], v[202:205], v[20:23]
	v_mfma_f32_16x16x32_bf16 v[16:19], v[176:179], v[202:205], v[16:19]
	v_mfma_f32_16x16x32_bf16 v[4:7], v[160:163], v[214:217], v[4:7]
	v_mfma_f32_16x16x32_bf16 v[0:3], v[176:179], v[214:217], v[0:3]
	v_mfma_f32_16x16x32_bf16 v[52:55], v[172:175], v[188:191], v[52:55]
	v_mfma_f32_16x16x32_bf16 v[48:51], v[180:183], v[188:191], v[48:51]
	v_mfma_f32_16x16x32_bf16 v[36:39], v[172:175], v[196:199], v[36:39]
	v_mfma_f32_16x16x32_bf16 v[32:35], v[180:183], v[196:199], v[32:35]
	v_mfma_f32_16x16x32_bf16 v[20:23], v[172:175], v[210:213], v[20:23]
	v_mfma_f32_16x16x32_bf16 v[16:19], v[180:183], v[210:213], v[16:19]
	v_mfma_f32_16x16x32_bf16 v[4:7], v[172:175], v[218:221], v[4:7]
	v_mfma_f32_16x16x32_bf16 v[0:3], v[180:183], v[218:221], v[0:3]
	s_barrier
	s_setprio 0
	s_add_i32 s38, 0, 0x18000
	s_add_i32 s39, 0, 0x1c000
	v_add_u32_e32 v156, s38, v169
	v_add_u32_e32 v180, s39, v169
	ds_read_b128 v[130:133], v156
	ds_read_b128 v[134:137], v156 offset:1024
	ds_read_b128 v[152:155], v156 offset:2048
	ds_read_b128 v[156:159], v156 offset:3072
	ds_read_b128 v[160:163], v180
	ds_read_b128 v[172:175], v180 offset:1024
	ds_read_b128 v[176:179], v180 offset:2048
	ds_read_b128 v[180:183], v180 offset:3072
	s_add_u32 s34, s86, 0x80000
	s_addc_u32 s35, s87, 0
	s_mov_b32 m0, s79
	ds_read_b128 v[184:187], v171 offset:32768
	ds_read_b128 v[188:191], v171 offset:33792
	ds_read_b128 v[192:195], v171 offset:34816
	ds_read_b128 v[196:199], v171 offset:35840
	ds_read_b128 v[202:205], v171 offset:36864
	ds_read_b128 v[210:213], v171 offset:37888
	ds_read_b128 v[214:217], v171 offset:38912
	ds_read_b128 v[218:221], v171 offset:39936
	global_load_lds_dwordx4 v146, s[34:35]
	s_mov_b32 m0, s90
	s_nop 0
	global_load_lds_dwordx4 v144, s[34:35]
	s_waitcnt vmcnt(8)
	s_waitcnt lgkmcnt(0)
	s_setprio 1
	s_barrier
	v_mfma_f32_16x16x32_bf16 v[126:129], v[130:133], v[184:187], v[126:129]
	v_mfma_f32_16x16x32_bf16 v[122:125], v[152:155], v[184:187], v[122:125]
	v_mfma_f32_16x16x32_bf16 v[110:113], v[130:133], v[192:195], v[110:113]
	v_mfma_f32_16x16x32_bf16 v[106:109], v[152:155], v[192:195], v[106:109]
	v_mfma_f32_16x16x32_bf16 v[92:95], v[130:133], v[202:205], v[92:95]
	v_mfma_f32_16x16x32_bf16 v[88:91], v[152:155], v[202:205], v[88:91]
	v_mfma_f32_16x16x32_bf16 v[76:79], v[130:133], v[214:217], v[76:79]
	v_mfma_f32_16x16x32_bf16 v[72:75], v[152:155], v[214:217], v[72:75]
	v_mfma_f32_16x16x32_bf16 v[126:129], v[134:137], v[188:191], v[126:129]
	v_mfma_f32_16x16x32_bf16 v[122:125], v[156:159], v[188:191], v[122:125]
	v_mfma_f32_16x16x32_bf16 v[110:113], v[134:137], v[196:199], v[110:113]
	v_mfma_f32_16x16x32_bf16 v[106:109], v[156:159], v[196:199], v[106:109]
	v_mfma_f32_16x16x32_bf16 v[92:95], v[134:137], v[210:213], v[92:95]
	v_mfma_f32_16x16x32_bf16 v[88:91], v[156:159], v[210:213], v[88:91]
	v_mfma_f32_16x16x32_bf16 v[76:79], v[134:137], v[218:221], v[76:79]
	v_mfma_f32_16x16x32_bf16 v[72:75], v[156:159], v[218:221], v[72:75]
	v_mfma_f32_16x16x32_bf16 v[118:121], v[160:163], v[184:187], v[118:121]
	v_mfma_f32_16x16x32_bf16 v[114:117], v[176:179], v[184:187], v[114:117]
	v_mfma_f32_16x16x32_bf16 v[102:105], v[160:163], v[192:195], v[102:105]
	v_mfma_f32_16x16x32_bf16 v[98:101], v[176:179], v[192:195], v[98:101]
	v_mfma_f32_16x16x32_bf16 v[84:87], v[160:163], v[202:205], v[84:87]
	v_mfma_f32_16x16x32_bf16 v[80:83], v[176:179], v[202:205], v[80:83]
	v_mfma_f32_16x16x32_bf16 v[68:71], v[160:163], v[214:217], v[68:71]
	v_mfma_f32_16x16x32_bf16 v[64:67], v[176:179], v[214:217], v[64:67]
	v_mfma_f32_16x16x32_bf16 v[118:121], v[172:175], v[188:191], v[118:121]
	v_mfma_f32_16x16x32_bf16 v[114:117], v[180:183], v[188:191], v[114:117]
	v_mfma_f32_16x16x32_bf16 v[102:105], v[172:175], v[196:199], v[102:105]
	v_mfma_f32_16x16x32_bf16 v[98:101], v[180:183], v[196:199], v[98:101]
	v_mfma_f32_16x16x32_bf16 v[84:87], v[172:175], v[210:213], v[84:87]
	v_mfma_f32_16x16x32_bf16 v[80:83], v[180:183], v[210:213], v[80:83]
	v_mfma_f32_16x16x32_bf16 v[68:71], v[172:175], v[218:221], v[68:71]
	v_mfma_f32_16x16x32_bf16 v[64:67], v[180:183], v[218:221], v[64:67]
	s_barrier
	s_setprio 0
	s_add_i32 s34, s38, s75
	s_add_i32 m0, s34, 0xffffff80
	ds_read_b128 v[184:187], v171 offset:49152
	ds_read_b128 v[188:191], v171 offset:50176
	ds_read_b128 v[192:195], v171 offset:51200
	ds_read_b128 v[196:199], v171 offset:52224
	ds_read_b128 v[202:205], v171 offset:53248
	ds_read_b128 v[210:213], v171 offset:54272
	ds_read_b128 v[214:217], v171 offset:55296
	ds_read_b128 v[218:221], v171 offset:56320
	global_load_lds_dwordx4 v96, s[84:85] offset:128
	s_add_i32 m0, s34, 0x1f80
	s_add_u32 s34, s84, 0x80080
	s_addc_u32 s35, s85, 0
	s_add_i32 s38, s39, s75
	global_load_lds_dwordx4 v142, s[84:85] offset:128
	s_mov_b32 m0, s38
	s_nop 0
	global_load_lds_dwordx4 v96, s[34:35]
	s_add_i32 m0, s38, 0x2000
	s_nop 0
	global_load_lds_dwordx4 v142, s[34:35]
	s_add_i32 m0, s94, 0xffffff80
	s_nop 0
	global_load_lds_dwordx4 v146, s[86:87] offset:128
	s_add_i32 m0, s95, 0xffffff80
	s_nop 0
	global_load_lds_dwordx4 v144, s[86:87] offset:128
	s_waitcnt vmcnt(8)
	s_waitcnt lgkmcnt(0)
	s_setprio 1
	s_barrier
	v_mfma_f32_16x16x32_bf16 v[60:63], v[130:133], v[184:187], v[60:63]
	v_mfma_f32_16x16x32_bf16 v[56:59], v[152:155], v[184:187], v[56:59]
	v_mfma_f32_16x16x32_bf16 v[44:47], v[130:133], v[192:195], v[44:47]
	v_mfma_f32_16x16x32_bf16 v[40:43], v[152:155], v[192:195], v[40:43]
	v_mfma_f32_16x16x32_bf16 v[28:31], v[130:133], v[202:205], v[28:31]
	v_mfma_f32_16x16x32_bf16 v[24:27], v[152:155], v[202:205], v[24:27]
	v_mfma_f32_16x16x32_bf16 v[12:15], v[130:133], v[214:217], v[12:15]
	v_mfma_f32_16x16x32_bf16 v[8:11], v[152:155], v[214:217], v[8:11]
	v_mfma_f32_16x16x32_bf16 v[60:63], v[134:137], v[188:191], v[60:63]
	v_mfma_f32_16x16x32_bf16 v[56:59], v[156:159], v[188:191], v[56:59]
	v_mfma_f32_16x16x32_bf16 v[44:47], v[134:137], v[196:199], v[44:47]
	v_mfma_f32_16x16x32_bf16 v[40:43], v[156:159], v[196:199], v[40:43]
	v_mfma_f32_16x16x32_bf16 v[28:31], v[134:137], v[210:213], v[28:31]
	v_mfma_f32_16x16x32_bf16 v[24:27], v[156:159], v[210:213], v[24:27]
	v_mfma_f32_16x16x32_bf16 v[12:15], v[134:137], v[218:221], v[12:15]
	v_mfma_f32_16x16x32_bf16 v[8:11], v[156:159], v[218:221], v[8:11]
	v_mfma_f32_16x16x32_bf16 v[52:55], v[160:163], v[184:187], v[52:55]
	v_mfma_f32_16x16x32_bf16 v[48:51], v[176:179], v[184:187], v[48:51]
	v_mfma_f32_16x16x32_bf16 v[36:39], v[160:163], v[192:195], v[36:39]
	v_mfma_f32_16x16x32_bf16 v[32:35], v[176:179], v[192:195], v[32:35]
	v_mfma_f32_16x16x32_bf16 v[20:23], v[160:163], v[202:205], v[20:23]
	v_mfma_f32_16x16x32_bf16 v[16:19], v[176:179], v[202:205], v[16:19]
	v_mfma_f32_16x16x32_bf16 v[4:7], v[160:163], v[214:217], v[4:7]
	v_mfma_f32_16x16x32_bf16 v[0:3], v[176:179], v[214:217], v[0:3]
	v_mfma_f32_16x16x32_bf16 v[52:55], v[172:175], v[188:191], v[52:55]
	v_mfma_f32_16x16x32_bf16 v[48:51], v[180:183], v[188:191], v[48:51]
	v_mfma_f32_16x16x32_bf16 v[36:39], v[172:175], v[196:199], v[36:39]
	v_mfma_f32_16x16x32_bf16 v[32:35], v[180:183], v[196:199], v[32:35]
	v_mfma_f32_16x16x32_bf16 v[20:23], v[172:175], v[210:213], v[20:23]
	v_mfma_f32_16x16x32_bf16 v[16:19], v[180:183], v[210:213], v[16:19]
	v_mfma_f32_16x16x32_bf16 v[4:7], v[172:175], v[218:221], v[4:7]
	v_mfma_f32_16x16x32_bf16 v[0:3], v[180:183], v[218:221], v[0:3]
	s_barrier
	s_setprio 0
	s_add_i32 s33, s33, 2
	s_add_u32 s44, s44, 0x100
	s_addc_u32 s45, s45, 0
	s_add_u32 s28, s28, 0x100
	s_addc_u32 s31, s31, 0
	s_cmp_gt_u32 s33, 29
	s_cbranch_scc0 .LBB0_1038
	v_mov_b32_e32 v243, 1
	v_readlane_b32 s0, v251, 54
	v_readlane_b32 s1, v251, 55
	s_and_b64 vcc, exec, s[0:1]
	s_cbranch_vccz .LBB0_1041
	s_barrier

.Lrx_G_DN_0:
	s_waitcnt vmcnt(44)
	s_waitcnt lgkmcnt(0)
	s_setprio 1
	s_barrier
	v_mfma_f32_16x16x32_bf16 v[126:129], v[144:147], v[184:187], v[126:129]
	v_mfma_f32_16x16x32_bf16 v[122:125], v[160:163], v[184:187], v[122:125]
	v_mfma_f32_16x16x32_bf16 v[110:113], v[144:147], v[192:195], v[110:113]
	v_mfma_f32_16x16x32_bf16 v[106:109], v[160:163], v[192:195], v[106:109]
	v_mfma_f32_16x16x32_bf16 v[92:95], v[144:147], v[202:205], v[92:95]
	v_mfma_f32_16x16x32_bf16 v[88:91], v[160:163], v[202:205], v[88:91]
	v_mfma_f32_16x16x32_bf16 v[76:79], v[144:147], v[214:217], v[76:79]
	v_mfma_f32_16x16x32_bf16 v[72:75], v[160:163], v[214:217], v[72:75]
	v_mfma_f32_16x16x32_bf16 v[126:129], v[154:157], v[188:191], v[126:129]
	v_mfma_f32_16x16x32_bf16 v[122:125], v[164:167], v[188:191], v[122:125]
	v_mfma_f32_16x16x32_bf16 v[110:113], v[154:157], v[196:199], v[110:113]
	v_mfma_f32_16x16x32_bf16 v[106:109], v[164:167], v[196:199], v[106:109]
	v_mfma_f32_16x16x32_bf16 v[92:95], v[154:157], v[210:213], v[92:95]
	v_mfma_f32_16x16x32_bf16 v[88:91], v[164:167], v[210:213], v[88:91]
	v_mfma_f32_16x16x32_bf16 v[76:79], v[154:157], v[218:221], v[76:79]
	v_mfma_f32_16x16x32_bf16 v[72:75], v[164:167], v[218:221], v[72:75]
	v_mfma_f32_16x16x32_bf16 v[118:121], v[168:171], v[184:187], v[118:121]
	v_mfma_f32_16x16x32_bf16 v[114:117], v[176:179], v[184:187], v[114:117]
	v_mfma_f32_16x16x32_bf16 v[102:105], v[168:171], v[192:195], v[102:105]
	v_mfma_f32_16x16x32_bf16 v[98:101], v[176:179], v[192:195], v[98:101]
	v_mfma_f32_16x16x32_bf16 v[84:87], v[168:171], v[202:205], v[84:87]
	v_mfma_f32_16x16x32_bf16 v[80:83], v[176:179], v[202:205], v[80:83]
	v_mfma_f32_16x16x32_bf16 v[68:71], v[168:171], v[214:217], v[68:71]
	v_mfma_f32_16x16x32_bf16 v[64:67], v[176:179], v[214:217], v[64:67]
	v_mfma_f32_16x16x32_bf16 v[118:121], v[172:175], v[188:191], v[118:121]
	v_mfma_f32_16x16x32_bf16 v[114:117], v[180:183], v[188:191], v[114:117]
	v_mfma_f32_16x16x32_bf16 v[102:105], v[172:175], v[196:199], v[102:105]
	v_mfma_f32_16x16x32_bf16 v[98:101], v[180:183], v[196:199], v[98:101]
	v_mfma_f32_16x16x32_bf16 v[84:87], v[172:175], v[210:213], v[84:87]
	v_mfma_f32_16x16x32_bf16 v[80:83], v[180:183], v[210:213], v[80:83]
	v_mfma_f32_16x16x32_bf16 v[68:71], v[172:175], v[218:221], v[68:71]
	v_mfma_f32_16x16x32_bf16 v[64:67], v[180:183], v[218:221], v[64:67]
	s_barrier
	s_setprio 0
	s_add_i32 s54, s54, s75
	s_mov_b32 m0, s54
	ds_read_b128 v[184:187], v159 offset:16384
	ds_read_b128 v[188:191], v159 offset:17408
	ds_read_b128 v[192:195], v159 offset:18432
	ds_read_b128 v[196:199], v159 offset:19456
	ds_read_b128 v[202:205], v159 offset:20480
	ds_read_b128 v[210:213], v159 offset:21504
	ds_read_b128 v[214:217], v159 offset:22528
	ds_read_b128 v[218:221], v159 offset:23552
	global_load_lds_dwordx4 v96, s[44:45]
	s_add_i32 m0, s54, 0x2000
	s_add_u32 s54, s44, 0x200000
	v_lshl_add_u64 v[222:223], s[44:45], 0, v[134:135]
	s_addc_u32 s55, s45, 0
	s_add_i32 s35, s35, s75
	global_load_lds_dwordx4 v134, s[44:45]
	s_mov_b32 m0, s35
	v_lshl_add_u64 v[226:227], s[52:53], 0, v[136:137]
	global_load_lds_dwordx4 v96, s[54:55]
	s_add_i32 m0, s35, 0x2000
	s_nop 0
	global_load_lds_dwordx4 v134, s[54:55]
	v_lshl_add_u64 v[224:225], s[52:53], 0, v[138:139]
	s_mov_b32 m0, s59
	s_nop 0
	global_load_lds_dwordx4 v138, s[52:53]
	s_mov_b32 m0, s68
	s_nop 0
	global_load_lds_dwordx4 v136, s[52:53]
	v_cmp_ne_u32_e32 vcc, 0, v243
	s_cbranch_vccnz .Lrx_G_DN_1
	s_waitcnt vmcnt(8)
.Lrx_G_DN_1:
	s_waitcnt vmcnt(44)
	v_mov_b32_e32 v243, 0
	s_waitcnt lgkmcnt(0)
	s_setprio 1
	s_barrier
	v_mfma_f32_16x16x32_bf16 v[60:63], v[144:147], v[184:187], v[60:63]
	v_mfma_f32_16x16x32_bf16 v[56:59], v[160:163], v[184:187], v[56:59]
	v_mfma_f32_16x16x32_bf16 v[44:47], v[144:147], v[192:195], v[44:47]
	v_mfma_f32_16x16x32_bf16 v[40:43], v[160:163], v[192:195], v[40:43]
	v_mfma_f32_16x16x32_bf16 v[28:31], v[144:147], v[202:205], v[28:31]
	v_mfma_f32_16x16x32_bf16 v[24:27], v[160:163], v[202:205], v[24:27]
	v_mfma_f32_16x16x32_bf16 v[12:15], v[144:147], v[214:217], v[12:15]
	v_mfma_f32_16x16x32_bf16 v[8:11], v[160:163], v[214:217], v[8:11]
	v_mfma_f32_16x16x32_bf16 v[60:63], v[154:157], v[188:191], v[60:63]
	v_mfma_f32_16x16x32_bf16 v[56:59], v[164:167], v[188:191], v[56:59]
	v_mfma_f32_16x16x32_bf16 v[44:47], v[154:157], v[196:199], v[44:47]
	v_mfma_f32_16x16x32_bf16 v[40:43], v[164:167], v[196:199], v[40:43]
	v_mfma_f32_16x16x32_bf16 v[28:31], v[154:157], v[210:213], v[28:31]
	v_mfma_f32_16x16x32_bf16 v[24:27], v[164:167], v[210:213], v[24:27]
	v_mfma_f32_16x16x32_bf16 v[12:15], v[154:157], v[218:221], v[12:15]
	v_mfma_f32_16x16x32_bf16 v[8:11], v[164:167], v[218:221], v[8:11]
	v_mfma_f32_16x16x32_bf16 v[52:55], v[168:171], v[184:187], v[52:55]
	v_mfma_f32_16x16x32_bf16 v[48:51], v[176:179], v[184:187], v[48:51]
	v_mfma_f32_16x16x32_bf16 v[36:39], v[168:171], v[192:195], v[36:39]
	v_mfma_f32_16x16x32_bf16 v[32:35], v[176:179], v[192:195], v[32:35]
	v_mfma_f32_16x16x32_bf16 v[20:23], v[168:171], v[202:205], v[20:23]
	v_mfma_f32_16x16x32_bf16 v[16:19], v[176:179], v[202:205], v[16:19]
	v_mfma_f32_16x16x32_bf16 v[4:7], v[168:171], v[214:217], v[4:7]
	v_mfma_f32_16x16x32_bf16 v[0:3], v[176:179], v[214:217], v[0:3]
	v_mfma_f32_16x16x32_bf16 v[52:55], v[172:175], v[188:191], v[52:55]
	v_mfma_f32_16x16x32_bf16 v[48:51], v[180:183], v[188:191], v[48:51]
	v_mfma_f32_16x16x32_bf16 v[36:39], v[172:175], v[196:199], v[36:39]
	v_mfma_f32_16x16x32_bf16 v[32:35], v[180:183], v[196:199], v[32:35]
	v_mfma_f32_16x16x32_bf16 v[20:23], v[172:175], v[210:213], v[20:23]
	v_mfma_f32_16x16x32_bf16 v[16:19], v[180:183], v[210:213], v[16:19]
	v_mfma_f32_16x16x32_bf16 v[4:7], v[172:175], v[218:221], v[4:7]
	v_mfma_f32_16x16x32_bf16 v[0:3], v[180:183], v[218:221], v[0:3]
	s_barrier
	s_setprio 0
	s_add_i32 s35, 0, 0x18000
	s_add_i32 s54, 0, 0x1c000
	v_add_u32_e32 v164, s35, v153
	v_add_u32_e32 v180, s54, v153
	ds_read_b128 v[144:147], v164
	ds_read_b128 v[154:157], v164 offset:1024
	ds_read_b128 v[160:163], v164 offset:2048
	ds_read_b128 v[164:167], v164 offset:3072
	ds_read_b128 v[168:171], v180
	ds_read_b128 v[172:175], v180 offset:1024
	ds_read_b128 v[176:179], v180 offset:2048
	ds_read_b128 v[180:183], v180 offset:3072
	s_add_u32 s52, s52, 0x200000
	s_addc_u32 s53, s53, 0
	s_mov_b32 m0, s69
	ds_read_b128 v[184:187], v159 offset:32768
	ds_read_b128 v[188:191], v159 offset:33792
	ds_read_b128 v[192:195], v159 offset:34816
	ds_read_b128 v[196:199], v159 offset:35840
	ds_read_b128 v[202:205], v159 offset:36864
	ds_read_b128 v[210:213], v159 offset:37888
	ds_read_b128 v[214:217], v159 offset:38912
	ds_read_b128 v[218:221], v159 offset:39936
	global_load_lds_dwordx4 v138, s[52:53]
	s_mov_b32 m0, s79
	s_nop 0
	global_load_lds_dwordx4 v136, s[52:53]
	s_waitcnt vmcnt(8)
	s_waitcnt lgkmcnt(0)
	s_setprio 1
	s_barrier
	v_mfma_f32_16x16x32_bf16 v[126:129], v[144:147], v[184:187], v[126:129]
	v_mfma_f32_16x16x32_bf16 v[122:125], v[160:163], v[184:187], v[122:125]
	v_mfma_f32_16x16x32_bf16 v[110:113], v[144:147], v[192:195], v[110:113]
	v_mfma_f32_16x16x32_bf16 v[106:109], v[160:163], v[192:195], v[106:109]
	v_mfma_f32_16x16x32_bf16 v[92:95], v[144:147], v[202:205], v[92:95]
	v_mfma_f32_16x16x32_bf16 v[88:91], v[160:163], v[202:205], v[88:91]
	v_mfma_f32_16x16x32_bf16 v[76:79], v[144:147], v[214:217], v[76:79]
	v_mfma_f32_16x16x32_bf16 v[72:75], v[160:163], v[214:217], v[72:75]
	v_mfma_f32_16x16x32_bf16 v[126:129], v[154:157], v[188:191], v[126:129]
	v_mfma_f32_16x16x32_bf16 v[122:125], v[164:167], v[188:191], v[122:125]
	v_mfma_f32_16x16x32_bf16 v[110:113], v[154:157], v[196:199], v[110:113]
	v_mfma_f32_16x16x32_bf16 v[106:109], v[164:167], v[196:199], v[106:109]
	v_mfma_f32_16x16x32_bf16 v[92:95], v[154:157], v[210:213], v[92:95]
	v_mfma_f32_16x16x32_bf16 v[88:91], v[164:167], v[210:213], v[88:91]
	v_mfma_f32_16x16x32_bf16 v[76:79], v[154:157], v[218:221], v[76:79]
	v_mfma_f32_16x16x32_bf16 v[72:75], v[164:167], v[218:221], v[72:75]
	v_mfma_f32_16x16x32_bf16 v[118:121], v[168:171], v[184:187], v[118:121]
	v_mfma_f32_16x16x32_bf16 v[114:117], v[176:179], v[184:187], v[114:117]
	v_mfma_f32_16x16x32_bf16 v[102:105], v[168:171], v[192:195], v[102:105]
	v_mfma_f32_16x16x32_bf16 v[98:101], v[176:179], v[192:195], v[98:101]
	v_mfma_f32_16x16x32_bf16 v[84:87], v[168:171], v[202:205], v[84:87]
	v_mfma_f32_16x16x32_bf16 v[80:83], v[176:179], v[202:205], v[80:83]
	v_mfma_f32_16x16x32_bf16 v[68:71], v[168:171], v[214:217], v[68:71]
	v_mfma_f32_16x16x32_bf16 v[64:67], v[176:179], v[214:217], v[64:67]
	v_mfma_f32_16x16x32_bf16 v[118:121], v[172:175], v[188:191], v[118:121]
	v_mfma_f32_16x16x32_bf16 v[114:117], v[180:183], v[188:191], v[114:117]
	v_mfma_f32_16x16x32_bf16 v[102:105], v[172:175], v[196:199], v[102:105]
	v_mfma_f32_16x16x32_bf16 v[98:101], v[180:183], v[196:199], v[98:101]
	v_mfma_f32_16x16x32_bf16 v[84:87], v[172:175], v[210:213], v[84:87]
	v_mfma_f32_16x16x32_bf16 v[80:83], v[180:183], v[210:213], v[80:83]
	v_mfma_f32_16x16x32_bf16 v[68:71], v[172:175], v[218:221], v[68:71]
	v_mfma_f32_16x16x32_bf16 v[64:67], v[180:183], v[218:221], v[64:67]
	s_barrier
	s_setprio 0
	s_add_i32 s35, s35, s75
	s_add_i32 m0, s35, 0xffffff80
	ds_read_b128 v[184:187], v159 offset:49152
	ds_read_b128 v[188:191], v159 offset:50176
	ds_read_b128 v[192:195], v159 offset:51200
	ds_read_b128 v[196:199], v159 offset:52224
	ds_read_b128 v[202:205], v159 offset:53248
	ds_read_b128 v[210:213], v159 offset:54272
	ds_read_b128 v[214:217], v159 offset:55296
	ds_read_b128 v[218:221], v159 offset:56320
	global_load_lds_dwordx4 v96, s[44:45] offset:128
	s_add_i32 m0, s35, 0x2000
	s_add_u32 s44, s44, 0x200080
	v_lshl_add_u64 v[148:149], v[222:223], 0, s[64:65]
	s_addc_u32 s45, s45, 0
	s_add_i32 s35, s54, s75
	global_load_lds_dwordx4 v[148:149], off
	s_mov_b32 m0, s35
	s_nop 0
	global_load_lds_dwordx4 v96, s[44:45]
	s_add_i32 m0, s35, 0x2000
	s_nop 0
	global_load_lds_dwordx4 v134, s[44:45]
	v_lshl_add_u64 v[148:149], v[224:225], 0, s[64:65]
	s_mov_b32 m0, s10
	s_nop 0
	global_load_lds_dwordx4 v[148:149], off
	v_lshl_add_u64 v[148:149], v[226:227], 0, s[64:65]
	s_mov_b32 m0, s77
	s_nop 0
	global_load_lds_dwordx4 v[148:149], off
	s_waitcnt vmcnt(8)
	s_waitcnt lgkmcnt(0)
	s_setprio 1
	s_barrier
	v_mfma_f32_16x16x32_bf16 v[60:63], v[144:147], v[184:187], v[60:63]
	v_mfma_f32_16x16x32_bf16 v[56:59], v[160:163], v[184:187], v[56:59]
	v_mfma_f32_16x16x32_bf16 v[44:47], v[144:147], v[192:195], v[44:47]
	v_mfma_f32_16x16x32_bf16 v[40:43], v[160:163], v[192:195], v[40:43]
	v_mfma_f32_16x16x32_bf16 v[28:31], v[144:147], v[202:205], v[28:31]
	v_mfma_f32_16x16x32_bf16 v[24:27], v[160:163], v[202:205], v[24:27]
	v_mfma_f32_16x16x32_bf16 v[12:15], v[144:147], v[214:217], v[12:15]
	v_mfma_f32_16x16x32_bf16 v[8:11], v[160:163], v[214:217], v[8:11]
	v_mfma_f32_16x16x32_bf16 v[60:63], v[154:157], v[188:191], v[60:63]
	v_mfma_f32_16x16x32_bf16 v[56:59], v[164:167], v[188:191], v[56:59]
	v_mfma_f32_16x16x32_bf16 v[44:47], v[154:157], v[196:199], v[44:47]
	v_mfma_f32_16x16x32_bf16 v[40:43], v[164:167], v[196:199], v[40:43]
	v_mfma_f32_16x16x32_bf16 v[28:31], v[154:157], v[210:213], v[28:31]
	v_mfma_f32_16x16x32_bf16 v[24:27], v[164:167], v[210:213], v[24:27]
	v_mfma_f32_16x16x32_bf16 v[12:15], v[154:157], v[218:221], v[12:15]
	v_mfma_f32_16x16x32_bf16 v[8:11], v[164:167], v[218:221], v[8:11]
	v_mfma_f32_16x16x32_bf16 v[52:55], v[168:171], v[184:187], v[52:55]
	v_mfma_f32_16x16x32_bf16 v[48:51], v[176:179], v[184:187], v[48:51]
	v_mfma_f32_16x16x32_bf16 v[36:39], v[168:171], v[192:195], v[36:39]
	v_mfma_f32_16x16x32_bf16 v[32:35], v[176:179], v[192:195], v[32:35]
	v_mfma_f32_16x16x32_bf16 v[20:23], v[168:171], v[202:205], v[20:23]
	v_mfma_f32_16x16x32_bf16 v[16:19], v[176:179], v[202:205], v[16:19]
	v_mfma_f32_16x16x32_bf16 v[4:7], v[168:171], v[214:217], v[4:7]
	v_mfma_f32_16x16x32_bf16 v[0:3], v[176:179], v[214:217], v[0:3]
	v_mfma_f32_16x16x32_bf16 v[52:55], v[172:175], v[188:191], v[52:55]
	v_mfma_f32_16x16x32_bf16 v[48:51], v[180:183], v[188:191], v[48:51]
	v_mfma_f32_16x16x32_bf16 v[36:39], v[172:175], v[196:199], v[36:39]
	v_mfma_f32_16x16x32_bf16 v[32:35], v[180:183], v[196:199], v[32:35]
	v_mfma_f32_16x16x32_bf16 v[20:23], v[172:175], v[210:213], v[20:23]
	v_mfma_f32_16x16x32_bf16 v[16:19], v[180:183], v[210:213], v[16:19]
	v_mfma_f32_16x16x32_bf16 v[4:7], v[172:175], v[218:221], v[4:7]
	v_mfma_f32_16x16x32_bf16 v[0:3], v[180:183], v[218:221], v[0:3]
	s_barrier
	s_setprio 0
	s_add_i32 s33, s33, 2
	s_add_u32 s42, s42, 0x100
	s_addc_u32 s43, s43, 0
	s_add_u32 s20, s20, 0x100
	s_addc_u32 s28, s28, 0
	s_cmpk_gt_u32 s33, 0x7d
	s_cbranch_scc0 .LBB0_1265
	v_mov_b32_e32 v243, 1
	v_readlane_b32 s6, v251, 54
	v_readlane_b32 s7, v251, 55
	s_and_b64 vcc, exec, s[6:7]
	s_movk_i32 s53, 0x6000
	s_cbranch_vccz .LBB0_1268
	s_barrier

.Lrx_G_UP_0:
	s_waitcnt vmcnt(24)
	s_waitcnt lgkmcnt(0)
	s_setprio 1
	s_barrier
	v_mfma_f32_16x16x32_bf16 v[126:129], v[154:157], v[186:189], v[126:129]
	v_mfma_f32_16x16x32_bf16 v[122:125], v[162:165], v[186:189], v[122:125]
	v_mfma_f32_16x16x32_bf16 v[110:113], v[154:157], v[194:197], v[110:113]
	v_mfma_f32_16x16x32_bf16 v[106:109], v[162:165], v[194:197], v[106:109]
	v_mfma_f32_16x16x32_bf16 v[92:95], v[154:157], v[210:213], v[92:95]
	v_mfma_f32_16x16x32_bf16 v[88:91], v[162:165], v[210:213], v[88:91]
	v_mfma_f32_16x16x32_bf16 v[76:79], v[154:157], v[218:221], v[76:79]
	v_mfma_f32_16x16x32_bf16 v[72:75], v[162:165], v[218:221], v[72:75]
	v_mfma_f32_16x16x32_bf16 v[126:129], v[158:161], v[190:193], v[126:129]
	v_mfma_f32_16x16x32_bf16 v[122:125], v[166:169], v[190:193], v[122:125]
	v_mfma_f32_16x16x32_bf16 v[110:113], v[158:161], v[202:205], v[110:113]
	v_mfma_f32_16x16x32_bf16 v[106:109], v[166:169], v[202:205], v[106:109]
	v_mfma_f32_16x16x32_bf16 v[92:95], v[158:161], v[214:217], v[92:95]
	v_mfma_f32_16x16x32_bf16 v[88:91], v[166:169], v[214:217], v[88:91]
	v_mfma_f32_16x16x32_bf16 v[76:79], v[158:161], v[222:225], v[76:79]
	v_mfma_f32_16x16x32_bf16 v[72:75], v[166:169], v[222:225], v[72:75]
	v_mfma_f32_16x16x32_bf16 v[118:121], v[170:173], v[186:189], v[118:121]
	v_mfma_f32_16x16x32_bf16 v[114:117], v[178:181], v[186:189], v[114:117]
	v_mfma_f32_16x16x32_bf16 v[102:105], v[170:173], v[194:197], v[102:105]
	v_mfma_f32_16x16x32_bf16 v[98:101], v[178:181], v[194:197], v[98:101]
	v_mfma_f32_16x16x32_bf16 v[84:87], v[170:173], v[210:213], v[84:87]
	v_mfma_f32_16x16x32_bf16 v[80:83], v[178:181], v[210:213], v[80:83]
	v_mfma_f32_16x16x32_bf16 v[68:71], v[170:173], v[218:221], v[68:71]
	v_mfma_f32_16x16x32_bf16 v[64:67], v[178:181], v[218:221], v[64:67]
	v_mfma_f32_16x16x32_bf16 v[118:121], v[174:177], v[190:193], v[118:121]
	v_mfma_f32_16x16x32_bf16 v[114:117], v[182:185], v[190:193], v[114:117]
	v_mfma_f32_16x16x32_bf16 v[102:105], v[174:177], v[202:205], v[102:105]
	v_mfma_f32_16x16x32_bf16 v[98:101], v[182:185], v[202:205], v[98:101]
	v_mfma_f32_16x16x32_bf16 v[84:87], v[174:177], v[214:217], v[84:87]
	v_mfma_f32_16x16x32_bf16 v[80:83], v[182:185], v[214:217], v[80:83]
	v_mfma_f32_16x16x32_bf16 v[68:71], v[174:177], v[222:225], v[68:71]
	v_mfma_f32_16x16x32_bf16 v[64:67], v[182:185], v[222:225], v[64:67]
	s_barrier
	s_setprio 0
	s_add_i32 s38, s39, s75
	s_mov_b32 m0, s38
	ds_read_b128 v[186:189], v152 offset:16384
	ds_read_b128 v[190:193], v152 offset:17408
	ds_read_b128 v[194:197], v152 offset:18432
	ds_read_b128 v[202:205], v152 offset:19456
	ds_read_b128 v[210:213], v152 offset:20480
	ds_read_b128 v[214:217], v152 offset:21504
	ds_read_b128 v[218:221], v152 offset:22528
	ds_read_b128 v[222:225], v152 offset:23552
	global_load_lds_dwordx4 v96, s[68:69]
	s_add_i32 m0, s38, 0x2000
	s_add_u32 s38, s68, 0x80000
	s_addc_u32 s39, s69, 0
	s_add_i32 s33, s33, s75
	global_load_lds_dwordx4 v134, s[68:69]
	s_mov_b32 m0, s33
	s_nop 0
	global_load_lds_dwordx4 v96, s[38:39]
	s_add_i32 m0, s33, 0x2000
	s_nop 0
	global_load_lds_dwordx4 v134, s[38:39]
	s_mov_b32 m0, s34
	s_nop 0
	global_load_lds_dwordx4 v138, s[82:83]
	s_mov_b32 m0, s35
	s_nop 0
	global_load_lds_dwordx4 v136, s[82:83]
	v_cmp_ne_u32_e32 vcc, 0, v243
	s_cbranch_vccnz .Lrx_G_UP_1
	s_waitcnt vmcnt(8)
.Lrx_G_UP_1:
	s_waitcnt vmcnt(24)
	v_mov_b32_e32 v243, 0
	s_waitcnt lgkmcnt(0)
	s_setprio 1
	s_barrier
	v_mfma_f32_16x16x32_bf16 v[60:63], v[154:157], v[186:189], v[60:63]
	v_mfma_f32_16x16x32_bf16 v[56:59], v[162:165], v[186:189], v[56:59]
	v_mfma_f32_16x16x32_bf16 v[44:47], v[154:157], v[194:197], v[44:47]
	v_mfma_f32_16x16x32_bf16 v[40:43], v[162:165], v[194:197], v[40:43]
	v_mfma_f32_16x16x32_bf16 v[28:31], v[154:157], v[210:213], v[28:31]
	v_mfma_f32_16x16x32_bf16 v[24:27], v[162:165], v[210:213], v[24:27]
	v_mfma_f32_16x16x32_bf16 v[12:15], v[154:157], v[218:221], v[12:15]
	v_mfma_f32_16x16x32_bf16 v[8:11], v[162:165], v[218:221], v[8:11]
	v_mfma_f32_16x16x32_bf16 v[60:63], v[158:161], v[190:193], v[60:63]
	v_mfma_f32_16x16x32_bf16 v[56:59], v[166:169], v[190:193], v[56:59]
	v_mfma_f32_16x16x32_bf16 v[44:47], v[158:161], v[202:205], v[44:47]
	v_mfma_f32_16x16x32_bf16 v[40:43], v[166:169], v[202:205], v[40:43]
	v_mfma_f32_16x16x32_bf16 v[28:31], v[158:161], v[214:217], v[28:31]
	v_mfma_f32_16x16x32_bf16 v[24:27], v[166:169], v[214:217], v[24:27]
	v_mfma_f32_16x16x32_bf16 v[12:15], v[158:161], v[222:225], v[12:15]
	v_mfma_f32_16x16x32_bf16 v[8:11], v[166:169], v[222:225], v[8:11]
	v_mfma_f32_16x16x32_bf16 v[52:55], v[170:173], v[186:189], v[52:55]
	v_mfma_f32_16x16x32_bf16 v[48:51], v[178:181], v[186:189], v[48:51]
	v_mfma_f32_16x16x32_bf16 v[36:39], v[170:173], v[194:197], v[36:39]
	v_mfma_f32_16x16x32_bf16 v[32:35], v[178:181], v[194:197], v[32:35]
	v_mfma_f32_16x16x32_bf16 v[20:23], v[170:173], v[210:213], v[20:23]
	v_mfma_f32_16x16x32_bf16 v[16:19], v[178:181], v[210:213], v[16:19]
	v_mfma_f32_16x16x32_bf16 v[4:7], v[170:173], v[218:221], v[4:7]
	v_mfma_f32_16x16x32_bf16 v[0:3], v[178:181], v[218:221], v[0:3]
	v_mfma_f32_16x16x32_bf16 v[52:55], v[174:177], v[190:193], v[52:55]
	v_mfma_f32_16x16x32_bf16 v[48:51], v[182:185], v[190:193], v[48:51]
	v_mfma_f32_16x16x32_bf16 v[36:39], v[174:177], v[202:205], v[36:39]
	v_mfma_f32_16x16x32_bf16 v[32:35], v[182:185], v[202:205], v[32:35]
	v_mfma_f32_16x16x32_bf16 v[20:23], v[174:177], v[214:217], v[20:23]
	v_mfma_f32_16x16x32_bf16 v[16:19], v[182:185], v[214:217], v[16:19]
	v_mfma_f32_16x16x32_bf16 v[4:7], v[174:177], v[222:225], v[4:7]
	v_mfma_f32_16x16x32_bf16 v[0:3], v[182:185], v[222:225], v[0:3]
	s_barrier
	s_setprio 0
	s_add_i32 s33, 0, 0x18000
	v_add_u32_e32 v153, s33, v150
	s_add_i32 s54, 0, 0x1c000
	ds_read_b128 v[154:157], v153
	ds_read_b128 v[158:161], v153 offset:1024
	ds_read_b128 v[162:165], v153 offset:2048
	ds_read_b128 v[166:169], v153 offset:3072
	v_add_u32_e32 v153, s54, v150
	ds_read_b128 v[170:173], v153
	ds_read_b128 v[174:177], v153 offset:1024
	ds_read_b128 v[178:181], v153 offset:2048
	ds_read_b128 v[182:185], v153 offset:3072
	s_add_u32 s38, s82, 0x80000
	s_addc_u32 s39, s83, 0
	s_mov_b32 m0, s50
	ds_read_b128 v[186:189], v152 offset:32768
	ds_read_b128 v[190:193], v152 offset:33792
	ds_read_b128 v[194:197], v152 offset:34816
	ds_read_b128 v[202:205], v152 offset:35840
	ds_read_b128 v[210:213], v152 offset:36864
	ds_read_b128 v[214:217], v152 offset:37888
	ds_read_b128 v[218:221], v152 offset:38912
	ds_read_b128 v[222:225], v152 offset:39936
	global_load_lds_dwordx4 v138, s[38:39]
	s_mov_b32 m0, s51
	s_nop 0
	global_load_lds_dwordx4 v136, s[38:39]
	s_waitcnt vmcnt(8)
	s_waitcnt lgkmcnt(0)
	s_setprio 1
	s_barrier
	v_mfma_f32_16x16x32_bf16 v[126:129], v[154:157], v[186:189], v[126:129]
	v_mfma_f32_16x16x32_bf16 v[122:125], v[162:165], v[186:189], v[122:125]
	v_mfma_f32_16x16x32_bf16 v[110:113], v[154:157], v[194:197], v[110:113]
	v_mfma_f32_16x16x32_bf16 v[106:109], v[162:165], v[194:197], v[106:109]
	v_mfma_f32_16x16x32_bf16 v[92:95], v[154:157], v[210:213], v[92:95]
	v_mfma_f32_16x16x32_bf16 v[88:91], v[162:165], v[210:213], v[88:91]
	v_mfma_f32_16x16x32_bf16 v[76:79], v[154:157], v[218:221], v[76:79]
	v_mfma_f32_16x16x32_bf16 v[72:75], v[162:165], v[218:221], v[72:75]
	v_mfma_f32_16x16x32_bf16 v[126:129], v[158:161], v[190:193], v[126:129]
	v_mfma_f32_16x16x32_bf16 v[122:125], v[166:169], v[190:193], v[122:125]
	v_mfma_f32_16x16x32_bf16 v[110:113], v[158:161], v[202:205], v[110:113]
	v_mfma_f32_16x16x32_bf16 v[106:109], v[166:169], v[202:205], v[106:109]
	v_mfma_f32_16x16x32_bf16 v[92:95], v[158:161], v[214:217], v[92:95]
	v_mfma_f32_16x16x32_bf16 v[88:91], v[166:169], v[214:217], v[88:91]
	v_mfma_f32_16x16x32_bf16 v[76:79], v[158:161], v[222:225], v[76:79]
	v_mfma_f32_16x16x32_bf16 v[72:75], v[166:169], v[222:225], v[72:75]
	v_mfma_f32_16x16x32_bf16 v[118:121], v[170:173], v[186:189], v[118:121]
	v_mfma_f32_16x16x32_bf16 v[114:117], v[178:181], v[186:189], v[114:117]
	v_mfma_f32_16x16x32_bf16 v[102:105], v[170:173], v[194:197], v[102:105]
	v_mfma_f32_16x16x32_bf16 v[98:101], v[178:181], v[194:197], v[98:101]
	v_mfma_f32_16x16x32_bf16 v[84:87], v[170:173], v[210:213], v[84:87]
	v_mfma_f32_16x16x32_bf16 v[80:83], v[178:181], v[210:213], v[80:83]
	v_mfma_f32_16x16x32_bf16 v[68:71], v[170:173], v[218:221], v[68:71]
	v_mfma_f32_16x16x32_bf16 v[64:67], v[178:181], v[218:221], v[64:67]
	v_mfma_f32_16x16x32_bf16 v[118:121], v[174:177], v[190:193], v[118:121]
	v_mfma_f32_16x16x32_bf16 v[114:117], v[182:185], v[190:193], v[114:117]
	v_mfma_f32_16x16x32_bf16 v[102:105], v[174:177], v[202:205], v[102:105]
	v_mfma_f32_16x16x32_bf16 v[98:101], v[182:185], v[202:205], v[98:101]
	v_mfma_f32_16x16x32_bf16 v[84:87], v[174:177], v[214:217], v[84:87]
	v_mfma_f32_16x16x32_bf16 v[80:83], v[182:185], v[214:217], v[80:83]
	v_mfma_f32_16x16x32_bf16 v[68:71], v[174:177], v[222:225], v[68:71]
	v_mfma_f32_16x16x32_bf16 v[64:67], v[182:185], v[222:225], v[64:67]
	s_barrier
	s_setprio 0
	s_add_i32 s33, s33, s75
	s_add_i32 m0, s33, 0xffffff80
	ds_read_b128 v[186:189], v152 offset:49152
	ds_read_b128 v[190:193], v152 offset:50176
	ds_read_b128 v[194:197], v152 offset:51200
	ds_read_b128 v[202:205], v152 offset:52224
	ds_read_b128 v[210:213], v152 offset:53248
	ds_read_b128 v[214:217], v152 offset:54272
	ds_read_b128 v[218:221], v152 offset:55296
	ds_read_b128 v[222:225], v152 offset:56320
	global_load_lds_dwordx4 v96, s[68:69] offset:128
	s_add_i32 m0, s33, 0x1f80
	s_add_u32 s38, s68, 0x80080
	s_addc_u32 s39, s69, 0
	s_add_i32 s33, s54, s75
	global_load_lds_dwordx4 v134, s[68:69] offset:128
	s_mov_b32 m0, s33
	s_nop 0
	global_load_lds_dwordx4 v96, s[38:39]
	s_add_i32 m0, s33, 0x2000
	s_nop 0
	global_load_lds_dwordx4 v134, s[38:39]
	s_add_i32 m0, s58, 0xffffff80
	s_nop 0
	global_load_lds_dwordx4 v138, s[82:83] offset:128
	s_add_i32 m0, s59, 0xffffff80
	s_nop 0
	global_load_lds_dwordx4 v136, s[82:83] offset:128
	s_waitcnt vmcnt(8)
	s_waitcnt lgkmcnt(0)
	s_setprio 1
	s_barrier
	v_mfma_f32_16x16x32_bf16 v[60:63], v[154:157], v[186:189], v[60:63]
	v_mfma_f32_16x16x32_bf16 v[56:59], v[162:165], v[186:189], v[56:59]
	v_mfma_f32_16x16x32_bf16 v[44:47], v[154:157], v[194:197], v[44:47]
	v_mfma_f32_16x16x32_bf16 v[40:43], v[162:165], v[194:197], v[40:43]
	v_mfma_f32_16x16x32_bf16 v[28:31], v[154:157], v[210:213], v[28:31]
	v_mfma_f32_16x16x32_bf16 v[24:27], v[162:165], v[210:213], v[24:27]
	v_mfma_f32_16x16x32_bf16 v[12:15], v[154:157], v[218:221], v[12:15]
	v_mfma_f32_16x16x32_bf16 v[8:11], v[162:165], v[218:221], v[8:11]
	v_mfma_f32_16x16x32_bf16 v[60:63], v[158:161], v[190:193], v[60:63]
	v_mfma_f32_16x16x32_bf16 v[56:59], v[166:169], v[190:193], v[56:59]
	v_mfma_f32_16x16x32_bf16 v[44:47], v[158:161], v[202:205], v[44:47]
	v_mfma_f32_16x16x32_bf16 v[40:43], v[166:169], v[202:205], v[40:43]
	v_mfma_f32_16x16x32_bf16 v[28:31], v[158:161], v[214:217], v[28:31]
	v_mfma_f32_16x16x32_bf16 v[24:27], v[166:169], v[214:217], v[24:27]
	v_mfma_f32_16x16x32_bf16 v[12:15], v[158:161], v[222:225], v[12:15]
	v_mfma_f32_16x16x32_bf16 v[8:11], v[166:169], v[222:225], v[8:11]
	v_mfma_f32_16x16x32_bf16 v[52:55], v[170:173], v[186:189], v[52:55]
	v_mfma_f32_16x16x32_bf16 v[48:51], v[178:181], v[186:189], v[48:51]
	v_mfma_f32_16x16x32_bf16 v[36:39], v[170:173], v[194:197], v[36:39]
	v_mfma_f32_16x16x32_bf16 v[32:35], v[178:181], v[194:197], v[32:35]
	v_mfma_f32_16x16x32_bf16 v[20:23], v[170:173], v[210:213], v[20:23]
	v_mfma_f32_16x16x32_bf16 v[16:19], v[178:181], v[210:213], v[16:19]
	v_mfma_f32_16x16x32_bf16 v[4:7], v[170:173], v[218:221], v[4:7]
	v_mfma_f32_16x16x32_bf16 v[0:3], v[178:181], v[218:221], v[0:3]
	v_mfma_f32_16x16x32_bf16 v[52:55], v[174:177], v[190:193], v[52:55]
	v_mfma_f32_16x16x32_bf16 v[48:51], v[182:185], v[190:193], v[48:51]
	v_mfma_f32_16x16x32_bf16 v[36:39], v[174:177], v[202:205], v[36:39]
	v_mfma_f32_16x16x32_bf16 v[32:35], v[182:185], v[202:205], v[32:35]
	v_mfma_f32_16x16x32_bf16 v[20:23], v[174:177], v[214:217], v[20:23]
	v_mfma_f32_16x16x32_bf16 v[16:19], v[182:185], v[214:217], v[16:19]
	v_mfma_f32_16x16x32_bf16 v[4:7], v[174:177], v[222:225], v[4:7]
	v_mfma_f32_16x16x32_bf16 v[0:3], v[182:185], v[222:225], v[0:3]
	s_barrier
	s_setprio 0
	s_add_i32 s28, s28, 2
	s_add_u32 s52, s52, 0x100
	s_addc_u32 s53, s53, 0
	s_add_u32 s20, s20, 0x100
	s_addc_u32 s25, s25, 0
	s_cmp_gt_u32 s28, 29
	s_cbranch_scc0 .LBB0_1284
	v_mov_b32_e32 v243, 1
	v_readlane_b32 s6, v251, 54
	v_readlane_b32 s7, v251, 55
	s_and_b64 vcc, exec, s[6:7]
	s_cbranch_vccz .LBB0_1287
	s_barrier
